# scan block prologue de-serialised: the token loop's first LDS fragment reads are issued right after the per-block barrier, ahead of the output store and the next-block load ladder
# baseline (speedup 1.0000x reference)
.LBB0_346:
	v_lshl_add_u32 v41, s60, 2, v45
	s_waitcnt lgkmcnt(4)
	v_sub_f32_e32 v53, v53, v92
	v_fma_f32 v94, v53, v60, v92
	v_sub_f32_e32 v53, v54, v92
	v_fma_f32 v95, v53, v61, v92
	v_sub_f32_e32 v53, v55, v92
	v_fma_f32 v96, v53, v62, v92
	v_sub_f32_e32 v53, v56, v92
	v_fma_f32 v97, v53, v63, v92
	v_sub_f32_e32 v53, v57, v92
	v_fma_f32 v98, v53, v64, v92
	v_sub_f32_e32 v53, v58, v92
	v_fma_f32 v99, v53, v65, v92
	v_sub_f32_e32 v53, v59, v92
	v_sub_f32_e32 v52, v52, v92
	v_fma_f32 v100, v53, v66, v92
	v_fma_f32 v92, v52, v67, v92
	s_nop 0
	v_mul_f32_e32 v52, v71, v97
	v_mul_f32_e32 v53, v75, v92
	v_fmac_f32_e32 v52, v96, v70
	v_fmac_f32_e32 v53, v100, v74
	v_fmac_f32_e32 v52, v95, v69
	v_fmac_f32_e32 v53, v99, v73
	s_nop 0
	v_fmac_f32_e32 v52, v94, v68
	v_fmac_f32_e32 v53, v98, v72
	v_add_f32_e32 v101, v52, v53
	ds_read_b128 v[52:55], v21 offset:9216
	ds_read_b128 v[56:59], v21 offset:9472
	ds_read_b128 v[60:63], v21 offset:1024
	ds_read_b128 v[64:67], v21 offset:1280
	ds_read_b32 v102, v44 offset:24704
	v_sub_f32_e32 v68, v94, v93
	s_waitcnt lgkmcnt(8)
	v_fma_f32 v94, v68, v76, v93
	v_sub_f32_e32 v68, v95, v93
	v_fma_f32 v95, v68, v77, v93
	v_sub_f32_e32 v68, v96, v93
	v_fma_f32 v96, v68, v78, v93
	v_sub_f32_e32 v68, v97, v93
	v_fma_f32 v97, v68, v79, v93
	v_sub_f32_e32 v68, v98, v93
	s_waitcnt lgkmcnt(7)
	v_fma_f32 v98, v68, v80, v93
	v_sub_f32_e32 v68, v99, v93
	v_fma_f32 v99, v68, v81, v93
	v_sub_f32_e32 v68, v100, v93
	v_fma_f32 v100, v68, v82, v93
	v_sub_f32_e32 v68, v92, v93
	v_fmac_f32_e32 v93, v68, v83
	s_waitcnt lgkmcnt(6)
	v_mul_f32_e32 v68, v87, v97
	s_waitcnt lgkmcnt(5)
	v_mul_f32_e32 v69, v91, v93
	v_fmac_f32_e32 v68, v96, v86
	v_fmac_f32_e32 v69, v100, v90
	v_fmac_f32_e32 v68, v95, v85
	v_fmac_f32_e32 v69, v99, v89
	s_nop 0
	v_fmac_f32_e32 v68, v94, v84
	v_fmac_f32_e32 v69, v98, v88
	v_add_f32_e32 v84, v68, v69
	ds_read_b128 v[68:71], v21 offset:9728
	ds_read_b128 v[72:75], v21 offset:9984
	ds_read_b128 v[76:79], v21 offset:1536
	ds_read_b128 v[80:83], v21 offset:1792
	ds_read_b32 v85, v44 offset:24768
	s_waitcnt lgkmcnt(5)
	v_sub_f32_e32 v86, v94, v102
	v_fma_f32 v86, v86, v52, v102
	v_sub_f32_e32 v52, v95, v102
	v_fma_f32 v87, v52, v53, v102
	v_sub_f32_e32 v52, v96, v102
	v_fma_f32 v88, v52, v54, v102
	v_sub_f32_e32 v52, v97, v102
	v_fma_f32 v89, v52, v55, v102
	v_sub_f32_e32 v52, v98, v102
	v_fma_f32 v90, v52, v56, v102
	v_sub_f32_e32 v52, v99, v102
	v_fma_f32 v91, v52, v57, v102
	v_sub_f32_e32 v52, v100, v102
	v_fma_f32 v92, v52, v58, v102
	v_sub_f32_e32 v52, v93, v102
	v_fmac_f32_e32 v102, v52, v59
	s_nop 0
	v_mul_f32_e32 v52, v63, v89
	v_mul_f32_e32 v53, v67, v102
	v_fmac_f32_e32 v52, v88, v62
	v_fmac_f32_e32 v53, v92, v66
	v_fmac_f32_e32 v52, v87, v61
	v_fmac_f32_e32 v53, v91, v65
	s_nop 0
	v_fmac_f32_e32 v52, v86, v60
	v_fmac_f32_e32 v53, v90, v64
	v_add_f32_e32 v93, v52, v53
	ds_read_b128 v[52:55], v21 offset:10240
	ds_read_b128 v[56:59], v21 offset:10496
	ds_read_b128 v[60:63], v21 offset:2048
	ds_read_b128 v[64:67], v21 offset:2304
	ds_read_b32 v94, v44 offset:24832
	s_waitcnt lgkmcnt(5)
	v_sub_f32_e32 v86, v86, v85
	v_fma_f32 v86, v86, v68, v85
	v_sub_f32_e32 v68, v87, v85
	v_fma_f32 v87, v68, v69, v85
	v_sub_f32_e32 v68, v88, v85
	v_fma_f32 v88, v68, v70, v85
	v_sub_f32_e32 v68, v89, v85
	v_fma_f32 v89, v68, v71, v85
	v_sub_f32_e32 v68, v90, v85
	v_fma_f32 v90, v68, v72, v85
	v_sub_f32_e32 v68, v91, v85
	v_fma_f32 v91, v68, v73, v85
	v_sub_f32_e32 v68, v92, v85
	v_fma_f32 v92, v68, v74, v85
	v_sub_f32_e32 v68, v102, v85
	v_fmac_f32_e32 v85, v68, v75
	s_nop 0
	v_mul_f32_e32 v68, v79, v89
	v_mul_f32_e32 v69, v83, v85
	v_fmac_f32_e32 v68, v88, v78
	v_fmac_f32_e32 v69, v92, v82
	v_fmac_f32_e32 v68, v87, v77
	v_fmac_f32_e32 v69, v91, v81
	v_cndmask_b32_e64 v70, v101, v84, s[0:1]
	v_fmac_f32_e32 v68, v86, v76
	v_fmac_f32_e32 v69, v90, v80
	v_add_f32_e32 v68, v68, v69
	v_cndmask_b32_e64 v69, v84, v101, s[0:1]
	v_cndmask_b32_e64 v71, v68, v93, s[0:1]
	v_cndmask_b32_e64 v68, v93, v68, s[0:1]
	v_add_f32_dpp v69, v70, v69 quad_perm:[1,0,3,2] row_mask:0xf bank_mask:0xf bound_ctrl:1
	s_nop 0
	v_add_f32_dpp v68, v68, v71 quad_perm:[1,0,3,2] row_mask:0xf bank_mask:0xf bound_ctrl:1
	v_cndmask_b32_e64 v70, v68, v69, s[4:5]
	v_cndmask_b32_e64 v68, v69, v68, s[4:5]
	s_nop 1
	v_add_f32_dpp v68, v68, v70 quad_perm:[2,3,0,1] row_mask:0xf bank_mask:0xf bound_ctrl:1
	s_nop 1
	v_add_f32_dpp v68, v68, v68 row_ror:4 row_mask:0xf bank_mask:0xf bound_ctrl:1
	s_nop 1
	v_add_f32_dpp v68, v68, v68 row_ror:8 row_mask:0xf bank_mask:0xf bound_ctrl:1
	ds_write_b32 v41, v68 offset:25600
	ds_read_b128 v[68:71], v21 offset:10752
	ds_read_b128 v[72:75], v21 offset:11008
	ds_read_b128 v[76:79], v21 offset:2560
	ds_read_b128 v[80:83], v21 offset:2816
	ds_read_b32 v84, v44 offset:24896
	s_waitcnt lgkmcnt(6)
	v_sub_f32_e32 v86, v86, v94
	v_fma_f32 v86, v86, v52, v94
	v_sub_f32_e32 v52, v87, v94
	v_fma_f32 v87, v52, v53, v94
	v_sub_f32_e32 v52, v88, v94
	v_fma_f32 v88, v52, v54, v94
	v_sub_f32_e32 v52, v89, v94
	v_fma_f32 v89, v52, v55, v94
	v_sub_f32_e32 v52, v90, v94
	v_fma_f32 v90, v52, v56, v94
	v_sub_f32_e32 v52, v91, v94
	v_fma_f32 v91, v52, v57, v94
	v_sub_f32_e32 v52, v92, v94
	v_fma_f32 v92, v52, v58, v94
	v_sub_f32_e32 v52, v85, v94
	v_fmac_f32_e32 v94, v52, v59
	s_nop 0
	v_mul_f32_e32 v52, v63, v89
	v_mul_f32_e32 v53, v67, v94
	v_fmac_f32_e32 v52, v88, v62
	v_fmac_f32_e32 v53, v92, v66
	v_fmac_f32_e32 v52, v87, v61
	v_fmac_f32_e32 v53, v91, v65
	s_nop 0
	v_fmac_f32_e32 v52, v86, v60
	v_fmac_f32_e32 v53, v90, v64
	v_add_f32_e32 v85, v52, v53
	ds_read_b128 v[52:55], v21 offset:11264
	ds_read_b128 v[56:59], v21 offset:11520
	ds_read_b128 v[60:63], v21 offset:3072
	ds_read_b128 v[64:67], v21 offset:3328
	ds_read_b32 v93, v44 offset:24960
	s_waitcnt lgkmcnt(5)
	v_sub_f32_e32 v86, v86, v84
	v_fma_f32 v86, v86, v68, v84
	v_sub_f32_e32 v68, v87, v84
	v_fma_f32 v87, v68, v69, v84
	v_sub_f32_e32 v68, v88, v84
	v_fma_f32 v88, v68, v70, v84
	v_sub_f32_e32 v68, v89, v84
	v_fma_f32 v89, v68, v71, v84
	v_sub_f32_e32 v68, v90, v84
	v_fma_f32 v90, v68, v72, v84
	v_sub_f32_e32 v68, v91, v84
	v_fma_f32 v91, v68, v73, v84
	v_sub_f32_e32 v68, v92, v84
	v_fma_f32 v92, v68, v74, v84
	v_sub_f32_e32 v68, v94, v84
	v_fmac_f32_e32 v84, v68, v75
	s_nop 0
	v_mul_f32_e32 v68, v79, v89
	v_mul_f32_e32 v69, v83, v84
	v_fmac_f32_e32 v68, v88, v78
	v_fmac_f32_e32 v69, v92, v82
	v_fmac_f32_e32 v68, v87, v77
	v_fmac_f32_e32 v69, v91, v81
	s_nop 0
	v_fmac_f32_e32 v68, v86, v76
	v_fmac_f32_e32 v69, v90, v80
	v_add_f32_e32 v94, v68, v69
	ds_read_b128 v[68:71], v21 offset:11776
	ds_read_b128 v[72:75], v21 offset:12032
	ds_read_b128 v[76:79], v21 offset:3584
	ds_read_b128 v[80:83], v21 offset:3840
	ds_read_b32 v95, v44 offset:25024
	s_waitcnt lgkmcnt(5)
	v_sub_f32_e32 v86, v86, v93
	v_fma_f32 v86, v86, v52, v93
	v_sub_f32_e32 v52, v87, v93
	v_fma_f32 v87, v52, v53, v93
	v_sub_f32_e32 v52, v88, v93
	v_fma_f32 v88, v52, v54, v93
	v_sub_f32_e32 v52, v89, v93
	v_fma_f32 v89, v52, v55, v93
	v_sub_f32_e32 v52, v90, v93
	v_fma_f32 v90, v52, v56, v93
	v_sub_f32_e32 v52, v91, v93
	v_fma_f32 v91, v52, v57, v93
	v_sub_f32_e32 v52, v92, v93
	v_fma_f32 v92, v52, v58, v93
	v_sub_f32_e32 v52, v84, v93
	v_fmac_f32_e32 v93, v52, v59
	s_nop 0
	v_mul_f32_e32 v52, v63, v89
	v_mul_f32_e32 v53, v67, v93
	v_fmac_f32_e32 v52, v88, v62
	v_fmac_f32_e32 v53, v92, v66
	v_fmac_f32_e32 v52, v87, v61
	v_fmac_f32_e32 v53, v91, v65
	s_nop 0
	v_fmac_f32_e32 v52, v86, v60
	v_fmac_f32_e32 v53, v90, v64
	v_add_f32_e32 v84, v52, v53
	ds_read_b128 v[52:55], v21 offset:12288
	ds_read_b128 v[56:59], v21 offset:12544
	ds_read_b128 v[60:63], v21 offset:4096
	ds_read_b128 v[64:67], v21 offset:4352
	ds_read_b32 v96, v44 offset:25088
	s_waitcnt lgkmcnt(5)
	v_sub_f32_e32 v86, v86, v95
	v_fma_f32 v86, v86, v68, v95
	v_sub_f32_e32 v68, v87, v95
	v_fma_f32 v87, v68, v69, v95
	v_sub_f32_e32 v68, v88, v95
	v_fma_f32 v88, v68, v70, v95
	v_sub_f32_e32 v68, v89, v95
	v_fma_f32 v89, v68, v71, v95
	v_sub_f32_e32 v68, v90, v95
	v_fma_f32 v90, v68, v72, v95
	v_sub_f32_e32 v68, v91, v95
	v_fma_f32 v91, v68, v73, v95
	v_sub_f32_e32 v68, v92, v95
	v_fma_f32 v92, v68, v74, v95
	v_sub_f32_e32 v68, v93, v95
	v_fmac_f32_e32 v95, v68, v75
	s_nop 0
	v_mul_f32_e32 v68, v79, v89
	v_mul_f32_e32 v69, v83, v95
	v_fmac_f32_e32 v68, v88, v78
	v_fmac_f32_e32 v69, v92, v82
	v_fmac_f32_e32 v68, v87, v77
	v_fmac_f32_e32 v69, v91, v81
	v_cndmask_b32_e64 v70, v85, v94, s[0:1]
	v_fmac_f32_e32 v68, v86, v76
	v_fmac_f32_e32 v69, v90, v80
	v_add_f32_e32 v68, v68, v69
	v_cndmask_b32_e64 v69, v94, v85, s[0:1]
	v_cndmask_b32_e64 v71, v68, v84, s[0:1]
	v_cndmask_b32_e64 v68, v84, v68, s[0:1]
	v_add_f32_dpp v69, v70, v69 quad_perm:[1,0,3,2] row_mask:0xf bank_mask:0xf bound_ctrl:1
	s_nop 0
	v_add_f32_dpp v68, v68, v71 quad_perm:[1,0,3,2] row_mask:0xf bank_mask:0xf bound_ctrl:1
	v_cndmask_b32_e64 v70, v68, v69, s[4:5]
	v_cndmask_b32_e64 v68, v69, v68, s[4:5]
	v_add_u32_e32 v69, v41, v47
	s_nop 0
	v_add_f32_dpp v68, v68, v70 quad_perm:[2,3,0,1] row_mask:0xf bank_mask:0xf bound_ctrl:1
	s_nop 1
	v_add_f32_dpp v68, v68, v68 row_ror:4 row_mask:0xf bank_mask:0xf bound_ctrl:1
	s_nop 1
	v_add_f32_dpp v68, v68, v68 row_ror:8 row_mask:0xf bank_mask:0xf bound_ctrl:1
	ds_write_b32 v69, v68 offset:25600
	ds_read_b128 v[68:71], v21 offset:12800
	ds_read_b128 v[72:75], v21 offset:13056
	ds_read_b128 v[76:79], v21 offset:4608
	ds_read_b128 v[80:83], v21 offset:4864
	ds_read_b32 v84, v44 offset:25152
	s_waitcnt lgkmcnt(6)
	v_sub_f32_e32 v85, v86, v96
	v_fma_f32 v85, v85, v52, v96
	v_sub_f32_e32 v52, v87, v96
	v_fma_f32 v86, v52, v53, v96
	v_sub_f32_e32 v52, v88, v96
	v_fma_f32 v87, v52, v54, v96
	v_sub_f32_e32 v52, v89, v96
	v_fma_f32 v88, v52, v55, v96
	v_sub_f32_e32 v52, v90, v96
	v_fma_f32 v89, v52, v56, v96
	v_sub_f32_e32 v52, v91, v96
	v_fma_f32 v90, v52, v57, v96
	v_sub_f32_e32 v52, v92, v96
	v_fma_f32 v91, v52, v58, v96
	v_sub_f32_e32 v52, v95, v96
	v_fmac_f32_e32 v96, v52, v59
	s_nop 0
	v_mul_f32_e32 v52, v63, v88
	v_mul_f32_e32 v53, v67, v96
	v_fmac_f32_e32 v52, v87, v62
	v_fmac_f32_e32 v53, v91, v66
	v_fmac_f32_e32 v52, v86, v61
	v_fmac_f32_e32 v53, v90, v65
	s_nop 0
	v_fmac_f32_e32 v52, v85, v60
	v_fmac_f32_e32 v53, v89, v64
	v_add_f32_e32 v92, v52, v53
	ds_read_b128 v[52:55], v21 offset:13312
	ds_read_b128 v[56:59], v21 offset:13568
	ds_read_b128 v[60:63], v21 offset:5120
	ds_read_b128 v[64:67], v21 offset:5376
	ds_read_b32 v93, v44 offset:25216
	s_waitcnt lgkmcnt(5)
	v_sub_f32_e32 v85, v85, v84
	v_fma_f32 v85, v85, v68, v84
	v_sub_f32_e32 v68, v86, v84
	v_fma_f32 v86, v68, v69, v84
	v_sub_f32_e32 v68, v87, v84
	v_fma_f32 v87, v68, v70, v84
	v_sub_f32_e32 v68, v88, v84
	v_fma_f32 v88, v68, v71, v84
	v_sub_f32_e32 v68, v89, v84
	v_fma_f32 v89, v68, v72, v84
	v_sub_f32_e32 v68, v90, v84
	v_fma_f32 v90, v68, v73, v84
	v_sub_f32_e32 v68, v91, v84
	v_fma_f32 v91, v68, v74, v84
	v_sub_f32_e32 v68, v96, v84
	v_fmac_f32_e32 v84, v68, v75
	s_nop 0
	v_mul_f32_e32 v68, v79, v88
	v_mul_f32_e32 v69, v83, v84
	v_fmac_f32_e32 v68, v87, v78
	v_fmac_f32_e32 v69, v91, v82
	v_fmac_f32_e32 v68, v86, v77
	v_fmac_f32_e32 v69, v90, v81
	s_nop 0
	v_fmac_f32_e32 v68, v85, v76
	v_fmac_f32_e32 v69, v89, v80
	v_add_f32_e32 v94, v68, v69
	ds_read_b128 v[68:71], v21 offset:13824
	ds_read_b128 v[72:75], v21 offset:14080
	ds_read_b128 v[76:79], v21 offset:5632
	ds_read_b128 v[80:83], v21 offset:5888
	ds_read_b32 v95, v44 offset:25280
	s_waitcnt lgkmcnt(5)
	v_sub_f32_e32 v85, v85, v93
	v_fma_f32 v85, v85, v52, v93
	v_sub_f32_e32 v52, v86, v93
	v_fma_f32 v86, v52, v53, v93
	v_sub_f32_e32 v52, v87, v93
	v_fma_f32 v87, v52, v54, v93
	v_sub_f32_e32 v52, v88, v93
	v_fma_f32 v88, v52, v55, v93
	v_sub_f32_e32 v52, v89, v93
	v_fma_f32 v89, v52, v56, v93
	v_sub_f32_e32 v52, v90, v93
	v_fma_f32 v90, v52, v57, v93
	v_sub_f32_e32 v52, v91, v93
	v_fma_f32 v91, v52, v58, v93
	v_sub_f32_e32 v52, v84, v93
	v_fmac_f32_e32 v93, v52, v59
	s_nop 0
	v_mul_f32_e32 v52, v63, v88
	v_mul_f32_e32 v53, v67, v93
	v_fmac_f32_e32 v52, v87, v62
	v_fmac_f32_e32 v53, v91, v66
	v_fmac_f32_e32 v52, v86, v61
	v_fmac_f32_e32 v53, v90, v65
	s_nop 0
	v_fmac_f32_e32 v52, v85, v60
	v_fmac_f32_e32 v53, v89, v64
	v_add_f32_e32 v84, v52, v53
	ds_read_b128 v[52:55], v21 offset:14336
	ds_read_b128 v[56:59], v21 offset:14592
	ds_read_b128 v[60:63], v21 offset:6144
	ds_read_b128 v[64:67], v21 offset:6400
	ds_read_b32 v96, v44 offset:25344
	s_waitcnt lgkmcnt(5)
	v_sub_f32_e32 v85, v85, v95
	v_fma_f32 v85, v85, v68, v95
	v_sub_f32_e32 v68, v86, v95
	v_fma_f32 v86, v68, v69, v95
	v_sub_f32_e32 v68, v87, v95
	v_fma_f32 v87, v68, v70, v95
	v_sub_f32_e32 v68, v88, v95
	v_fma_f32 v88, v68, v71, v95
	v_sub_f32_e32 v68, v89, v95
	v_fma_f32 v89, v68, v72, v95
	v_sub_f32_e32 v68, v90, v95
	v_fma_f32 v90, v68, v73, v95
	v_sub_f32_e32 v68, v91, v95
	v_fma_f32 v91, v68, v74, v95
	v_sub_f32_e32 v68, v93, v95
	v_fmac_f32_e32 v95, v68, v75
	s_nop 0
	v_mul_f32_e32 v68, v79, v88
	v_mul_f32_e32 v69, v83, v95
	v_fmac_f32_e32 v68, v87, v78
	v_fmac_f32_e32 v69, v91, v82
	v_fmac_f32_e32 v68, v86, v77
	v_fmac_f32_e32 v69, v90, v81
	v_cndmask_b32_e64 v70, v92, v94, s[0:1]
	v_fmac_f32_e32 v68, v85, v76
	v_fmac_f32_e32 v69, v89, v80
	v_add_f32_e32 v68, v68, v69
	v_cndmask_b32_e64 v69, v94, v92, s[0:1]
	v_cndmask_b32_e64 v71, v68, v84, s[0:1]
	v_cndmask_b32_e64 v68, v84, v68, s[0:1]
	v_add_f32_dpp v69, v70, v69 quad_perm:[1,0,3,2] row_mask:0xf bank_mask:0xf bound_ctrl:1
	s_nop 0
	v_add_f32_dpp v68, v68, v71 quad_perm:[1,0,3,2] row_mask:0xf bank_mask:0xf bound_ctrl:1
	v_cndmask_b32_e64 v70, v68, v69, s[4:5]
	v_cndmask_b32_e64 v68, v69, v68, s[4:5]
	v_add_u32_e32 v69, v41, v48
	s_nop 0
	v_add_f32_dpp v68, v68, v70 quad_perm:[2,3,0,1] row_mask:0xf bank_mask:0xf bound_ctrl:1
	s_nop 1
	v_add_f32_dpp v68, v68, v68 row_ror:4 row_mask:0xf bank_mask:0xf bound_ctrl:1
	s_nop 1
	v_add_f32_dpp v68, v68, v68 row_ror:8 row_mask:0xf bank_mask:0xf bound_ctrl:1
	ds_write_b32 v69, v68 offset:25600
	ds_read_b128 v[68:71], v21 offset:14848
	ds_read_b128 v[72:75], v21 offset:15104
	ds_read_b128 v[76:79], v21 offset:6656
	ds_read_b128 v[80:83], v21 offset:6912
	ds_read_b32 v92, v44 offset:25408
	s_waitcnt lgkmcnt(6)
	v_sub_f32_e32 v84, v85, v96
	v_fma_f32 v52, v84, v52, v96
	v_sub_f32_e32 v84, v86, v96
	v_fma_f32 v53, v84, v53, v96
	v_sub_f32_e32 v84, v87, v96
	v_fma_f32 v93, v84, v54, v96
	v_sub_f32_e32 v54, v88, v96
	v_fma_f32 v88, v54, v55, v96
	v_sub_f32_e32 v54, v89, v96
	v_fma_f32 v89, v54, v56, v96
	v_sub_f32_e32 v54, v90, v96
	v_fma_f32 v90, v54, v57, v96
	v_sub_f32_e32 v54, v91, v96
	v_fma_f32 v91, v54, v58, v96
	v_sub_f32_e32 v54, v95, v96
	v_fmac_f32_e32 v96, v54, v59
	s_nop 0
	v_mul_f32_e32 v54, v63, v88
	v_mul_f32_e32 v55, v67, v96
	v_fmac_f32_e32 v54, v93, v62
	v_fmac_f32_e32 v55, v91, v66
	v_fmac_f32_e32 v54, v53, v61
	v_fmac_f32_e32 v55, v90, v65
	s_nop 0
	v_fmac_f32_e32 v54, v52, v60
	v_fmac_f32_e32 v55, v89, v64
	v_add_f32_e32 v94, v54, v55
	ds_read_b128 v[54:57], v21 offset:15360
	ds_read_b128 v[58:61], v21 offset:15616
	ds_read_b128 v[62:65], v21 offset:7168
	ds_read_b128 v[84:87], v21 offset:7424
	ds_read_b32 v95, v44 offset:25472
	s_waitcnt lgkmcnt(5)
	v_sub_f32_e32 v52, v52, v92
	v_fma_f32 v97, v52, v68, v92
	v_sub_f32_e32 v52, v53, v92
	v_fma_f32 v53, v52, v69, v92
	v_sub_f32_e32 v52, v93, v92
	v_fma_f32 v93, v52, v70, v92
	v_sub_f32_e32 v52, v88, v92
	v_fma_f32 v88, v52, v71, v92
	v_sub_f32_e32 v52, v89, v92
	v_fma_f32 v89, v52, v72, v92
	v_sub_f32_e32 v52, v90, v92
	v_fma_f32 v90, v52, v73, v92
	v_sub_f32_e32 v52, v91, v92
	v_fma_f32 v91, v52, v74, v92
	v_sub_f32_e32 v52, v96, v92
	v_fmac_f32_e32 v92, v52, v75
	s_nop 0
	v_mul_f32_e32 v52, v79, v88
	v_mul_f32_e32 v66, v83, v92
	v_fmac_f32_e32 v52, v93, v78
	v_fmac_f32_e32 v66, v91, v82
	v_fmac_f32_e32 v52, v53, v77
	v_fmac_f32_e32 v66, v90, v81
	s_nop 0
	v_fmac_f32_e32 v52, v97, v76
	v_fmac_f32_e32 v66, v89, v80
	v_add_f32_e32 v82, v52, v66
	ds_read_b128 v[66:69], v21 offset:15872
	ds_read_b128 v[70:73], v21 offset:16128
	ds_read_b128 v[74:77], v21 offset:7680
	ds_read_b128 v[78:81], v21 offset:7936
	ds_read_b32 v52, v44 offset:25536
	s_waitcnt lgkmcnt(5)
	v_sub_f32_e32 v53, v53, v95
	v_fma_f32 v55, v53, v55, v95
	v_sub_f32_e32 v53, v93, v95
	v_fma_f32 v56, v53, v56, v95
	v_sub_f32_e32 v53, v88, v95
	v_fma_f32 v57, v53, v57, v95
	v_sub_f32_e32 v53, v89, v95
	v_fma_f32 v58, v53, v58, v95
	v_sub_f32_e32 v53, v90, v95
	v_fma_f32 v59, v53, v59, v95
	v_sub_f32_e32 v53, v91, v95
	v_sub_f32_e32 v83, v97, v95
	v_fma_f32 v60, v53, v60, v95
	v_sub_f32_e32 v53, v92, v95
	v_fma_f32 v54, v83, v54, v95
	v_fmac_f32_e32 v95, v53, v61
	s_nop 0
	v_mul_f32_e32 v53, v65, v57
	v_mul_f32_e32 v61, v87, v95
	v_fmac_f32_e32 v53, v56, v64
	v_fmac_f32_e32 v61, v60, v86
	v_fmac_f32_e32 v53, v55, v63
	v_fmac_f32_e32 v61, v59, v85
	s_nop 0
	v_fmac_f32_e32 v53, v54, v62
	v_fmac_f32_e32 v61, v58, v84
	v_add_f32_e32 v61, v53, v61
	s_waitcnt lgkmcnt(0)
	v_sub_f32_e32 v53, v54, v52
	v_sub_f32_e32 v54, v55, v52
	v_sub_f32_e32 v55, v56, v52
	v_sub_f32_e32 v56, v57, v52
	v_sub_f32_e32 v57, v58, v52
	v_sub_f32_e32 v58, v59, v52
	v_sub_f32_e32 v59, v60, v52
	v_sub_f32_e32 v60, v95, v52
	v_fma_f32 v53, v53, v66, v52
	v_fma_f32 v54, v54, v67, v52
	v_fma_f32 v55, v55, v68, v52
	v_fma_f32 v56, v56, v69, v52
	v_fma_f32 v57, v57, v70, v52
	v_fma_f32 v58, v58, v71, v52
	v_fma_f32 v59, v59, v72, v52
	v_fmac_f32_e32 v52, v60, v73
	s_nop 0
	v_mul_f32_e32 v60, v77, v56
	v_mul_f32_e32 v62, v81, v52
	v_fmac_f32_e32 v60, v55, v76
	v_fmac_f32_e32 v62, v59, v80
	v_fmac_f32_e32 v60, v54, v75
	v_fmac_f32_e32 v62, v58, v79
	v_cndmask_b32_e64 v63, v94, v82, s[0:1]
	v_fmac_f32_e32 v60, v53, v74
	v_fmac_f32_e32 v62, v57, v78
	v_add_f32_e32 v60, v60, v62
	v_cndmask_b32_e64 v62, v82, v94, s[0:1]
	v_cndmask_b32_e64 v64, v60, v61, s[0:1]
	v_cndmask_b32_e64 v60, v61, v60, s[0:1]
	v_add_f32_dpp v61, v63, v62 quad_perm:[1,0,3,2] row_mask:0xf bank_mask:0xf bound_ctrl:1
	v_add_u32_e32 v41, v41, v49
	v_add_f32_dpp v60, v60, v64 quad_perm:[1,0,3,2] row_mask:0xf bank_mask:0xf bound_ctrl:1
	v_cndmask_b32_e64 v62, v60, v61, s[4:5]
	v_cndmask_b32_e64 v60, v61, v60, s[4:5]
	s_nop 1
	v_add_f32_dpp v60, v60, v62 quad_perm:[2,3,0,1] row_mask:0xf bank_mask:0xf bound_ctrl:1
	s_nop 1
	v_add_f32_dpp v60, v60, v60 row_ror:4 row_mask:0xf bank_mask:0xf bound_ctrl:1
	s_nop 1
	v_add_f32_dpp v60, v60, v60 row_ror:8 row_mask:0xf bank_mask:0xf bound_ctrl:1
	ds_write_b32 v41, v60 offset:25600
	s_addk_i32 s31, 0x100
	s_add_i32 s30, s30, 1
	s_cmp_lg_u32 s59, s31
	v_add_u32_e32 v51, 16, v51
	s_waitcnt lgkmcnt(0)
	s_cbranch_scc0 .Lhg0_exitb
.LBB0_347:
	v_add_u32_e32 v15, s77, v15
	v_add_u32_e32 v17, s78, v17
	s_waitcnt vmcnt(0)
	v_lshlrev_b32_e32 v41, 16, v8
	v_mul_f32_e32 v41, 0xbfb8aa3b, v41
	v_and_b32_e32 v61, 0xffff0000, v8
	v_exp_f32_e32 v41, v41
	v_mul_f32_e32 v61, 0xbfb8aa3b, v61
	v_exp_f32_e32 v62, v61
	v_and_b32_e32 v63, 0xffff0000, v9
	v_add_f32_e32 v41, 1.0, v41
	v_rcp_f32_e32 v68, v41
	v_add_f32_e32 v41, 1.0, v62
	v_rcp_f32_e32 v69, v41
	v_lshlrev_b32_e32 v41, 16, v9
	v_mul_f32_e32 v41, 0xbfb8aa3b, v41
	v_exp_f32_e32 v41, v41
	v_mul_f32_e32 v63, 0xbfb8aa3b, v63
	v_exp_f32_e32 v64, v63
	v_and_b32_e32 v65, 0xffff0000, v10
	v_add_f32_e32 v41, 1.0, v41
	v_rcp_f32_e32 v70, v41
	v_add_f32_e32 v41, 1.0, v64
	v_rcp_f32_e32 v71, v41
	v_lshlrev_b32_e32 v41, 16, v10
	v_mul_f32_e32 v41, 0xbfb8aa3b, v41
	v_exp_f32_e32 v41, v41
	v_mul_f32_e32 v65, 0xbfb8aa3b, v65
	v_exp_f32_e32 v66, v65
	v_and_b32_e32 v67, 0xffff0000, v11
	v_add_f32_e32 v41, 1.0, v41
	v_rcp_f32_e32 v72, v41
	v_add_f32_e32 v41, 1.0, v66
	v_rcp_f32_e32 v73, v41
	v_lshlrev_b32_e32 v41, 16, v11
	v_mul_f32_e32 v41, 0xbfb8aa3b, v41
	v_exp_f32_e32 v41, v41
	v_mul_f32_e32 v67, 0xbfb8aa3b, v67
	v_exp_f32_e32 v75, v67
	v_lshlrev_b32_e32 v60, 16, v4
	v_add_f32_e32 v41, 1.0, v41
	v_rcp_f32_e32 v74, v41
	v_add_f32_e32 v41, 1.0, v75
	v_rcp_f32_e32 v75, v41
	v_and_b32_e32 v61, 0xffff0000, v4
	v_lshlrev_b32_e32 v62, 16, v5
	v_and_b32_e32 v63, 0xffff0000, v5
	v_lshlrev_b32_e32 v64, 16, v6
	v_and_b32_e32 v65, 0xffff0000, v6
	v_lshlrev_b32_e32 v66, 16, v7
	v_and_b32_e32 v67, 0xffff0000, v7
	s_and_b32 s60, s31, 0x100
	ds_write_b128 v15, v[60:63]
	ds_write_b128 v15, v[64:67] offset:16
	v_pk_fma_f32 v[60:61], v[30:31], v[68:69], v[22:23]
	v_pk_fma_f32 v[62:63], v[32:33], v[70:71], v[24:25]
	ds_write_b128 v15, v[60:63] offset:8192
	v_pk_fma_f32 v[60:61], v[34:35], v[72:73], v[26:27]
	v_pk_fma_f32 v[62:63], v[36:37], v[74:75], v[28:29]
	v_lshlrev_b32_e32 v41, 16, v39
	s_cmp_eq_u32 s31, 0
	ds_write_b128 v15, v[60:63] offset:8208
	ds_write_b32 v17, v41 offset:24576
	s_waitcnt lgkmcnt(0)
	s_barrier
	v_add_u32_e32 v21, s77, v21
	v_add_u32_e32 v44, s78, v44
	v_add_u32_e32 v50, s78, v50
	s_mul_i32 s77, s77, -1
	s_mul_i32 s78, s78, -1
	ds_read_b128 v[60:63], v21 offset:8192
	ds_read_b128 v[64:67], v21 offset:8448
	ds_read_b128 v[68:71], v21
	ds_read_b128 v[72:75], v21 offset:256
	ds_read2_b32 v[92:93], v50 offset1:16
	ds_read_b128 v[76:79], v21 offset:8704
	ds_read_b128 v[80:83], v21 offset:8960
	ds_read_b128 v[84:87], v21 offset:512
	ds_read_b128 v[88:91], v21 offset:768
	s_cbranch_scc1 .LBB0_349
	v_mov_b64_e32 v[122:123], s[46:47]
	v_mad_i64_i32 v[122:123], s[62:63], v51, s56, v[122:123]
	s_lshl_b32 s12, s29, 1
	v_lshl_add_u64 v[122:123], v[122:123], 0, s[12:13]
	s_lshl_b32 s12, s27, 1
	v_lshl_add_u64 v[122:123], v[122:123], 0, s[12:13]
	s_xor_b32 s12, s60, 0x100
	v_lshl_add_u32 v41, s12, 2, v46
	ds_read_b32 v41, v41 offset:25600
	v_lshl_add_u64 v[122:123], v[122:123], 0, v[2:3]
	v_add_co_u32_e32 v122, vcc, 0xfffd9000, v122
	s_waitcnt lgkmcnt(0)
	v_cvt_pk_bf16_f32 v41, v41, s0
	v_addc_co_u32_e32 v123, vcc, -1, v123, vcc
	global_store_short v[122:123], v41, off offset:-2560
.LBB0_349:
	s_cmp_ge_u32 s30, s28
	s_cbranch_scc1 .LBB0_346
	v_mov_b64_e32 v[4:5], s[46:47]
	v_mad_i64_i32 v[122:123], s[62:63], v51, s56, v[4:5]
	s_lshl_b32 s12, s29, 1
	v_mov_b32_e32 v39, v3
	v_lshl_add_u64 v[4:5], v[122:123], 0, s[12:13]
	v_lshl_add_u64 v[4:5], v[4:5], 0, v[38:39]
	v_add_co_u32_e32 v6, vcc, 0x2b000, v4
	v_mov_b32_e32 v41, v3
	s_nop 0
	v_addc_co_u32_e32 v7, vcc, 0, v5, vcc
	v_add_co_u32_e32 v8, vcc, 0x2c000, v4
	v_lshl_add_u64 v[122:123], v[122:123], 0, v[40:41]
	s_nop 0
	v_addc_co_u32_e32 v9, vcc, 0, v5, vcc
	v_add_co_u32_e32 v122, vcc, 0x2a000, v122
	global_load_dwordx4 v[4:7], v[6:7], off offset:3584
	s_nop 0
	global_load_dwordx4 v[8:11], v[8:9], off offset:512
	v_addc_co_u32_e32 v123, vcc, 0, v123, vcc
	global_load_ushort v39, v[122:123], off
	s_branch .LBB0_346

.LBB0_390:
	v_lshl_add_u32 v13, s24, 2, v36
	v_add_u32_e32 v2, v13, v34
	s_waitcnt lgkmcnt(9)
	v_mul_f32_e32 v29, v7, v57
	v_fmac_f32_e32 v29, v6, v56
	v_fmac_f32_e32 v29, v5, v55
	v_fmac_f32_e32 v29, v4, v54
	s_waitcnt lgkmcnt(3)
	v_mul_f32_e32 v53, v78, v94
	v_mul_f32_e32 v96, v79, v94
	v_add_f32_dpp v29, v29, v29 quad_perm:[1,0,3,2] row_mask:0xf bank_mask:0xf bound_ctrl:1
	v_mul_f32_e32 v97, v80, v94
	v_mul_f32_e32 v94, v81, v94
	v_add_f32_dpp v29, v29, v29 quad_perm:[2,3,0,1] row_mask:0xf bank_mask:0xf bound_ctrl:1
	s_nop 1
	v_add_f32_dpp v29, v29, v29 row_half_mirror row_mask:0xf bank_mask:0xf bound_ctrl:1
	s_nop 1
	v_add_f32_dpp v29, v29, v29 row_mirror row_mask:0xf bank_mask:0xf bound_ctrl:1
	v_fmac_f32_e32 v94, v29, v73
	v_fmac_f32_e32 v97, v29, v72
	v_fmac_f32_e32 v94, v7, v65
	v_fmac_f32_e32 v53, v29, v70
	v_fmac_f32_e32 v96, v29, v71
	v_fmac_f32_e32 v97, v6, v64
	v_fmac_f32_e32 v96, v5, v63
	s_waitcnt lgkmcnt(1)
	v_mul_f32_e32 v29, v89, v94
	v_fmac_f32_e32 v53, v4, v62
	v_fmac_f32_e32 v29, v97, v88
	s_nop 0
	v_fmac_f32_e32 v29, v96, v87
	v_fmac_f32_e32 v29, v53, v86
	ds_read_b128 v[4:7], v30 offset:12800
	ds_read_b128 v[54:57], v30 offset:8704
	ds_read_b128 v[62:65], v30 offset:4608
	ds_read_b128 v[70:73], v30 offset:512
	ds_read_b128 v[78:81], v30 offset:16896
	ds_read_b32 v98, v33 offset:20608
	v_mul_f32_e32 v61, v61, v94
	v_fmac_f32_e32 v61, v97, v60
	v_fmac_f32_e32 v61, v96, v59
	v_fmac_f32_e32 v61, v53, v58
	v_add_f32_dpp v29, v29, v29 quad_perm:[1,0,3,2] row_mask:0xf bank_mask:0xf bound_ctrl:1
	v_mul_f32_e32 v99, v82, v95
	v_add_f32_dpp v58, v61, v61 quad_perm:[1,0,3,2] row_mask:0xf bank_mask:0xf bound_ctrl:1
	v_add_f32_dpp v29, v29, v29 quad_perm:[2,3,0,1] row_mask:0xf bank_mask:0xf bound_ctrl:1
	s_nop 0
	v_add_f32_dpp v58, v58, v58 quad_perm:[2,3,0,1] row_mask:0xf bank_mask:0xf bound_ctrl:1
	v_add_f32_dpp v29, v29, v29 row_half_mirror row_mask:0xf bank_mask:0xf bound_ctrl:1
	s_nop 0
	v_add_f32_dpp v58, v58, v58 row_half_mirror row_mask:0xf bank_mask:0xf bound_ctrl:1
	v_add_f32_dpp v29, v29, v29 row_mirror row_mask:0xf bank_mask:0xf bound_ctrl:1
	ds_write_b32 v13, v29 offset:21504
	s_nop 0
	v_add_f32_dpp v29, v58, v58 row_mirror row_mask:0xf bank_mask:0xf bound_ctrl:1
	v_fmac_f32_e32 v99, v29, v74
	v_fmac_f32_e32 v99, v53, v66
	v_mul_f32_e32 v53, v83, v95
	v_fmac_f32_e32 v53, v29, v75
	v_fmac_f32_e32 v53, v96, v67
	v_mul_f32_e32 v96, v84, v95
	v_mul_f32_e32 v95, v85, v95
	v_fmac_f32_e32 v95, v29, v77
	v_fmac_f32_e32 v96, v29, v76
	v_fmac_f32_e32 v95, v94, v69
	v_fmac_f32_e32 v96, v97, v68
	s_waitcnt lgkmcnt(7)
	v_mul_f32_e32 v29, v93, v95
	v_fmac_f32_e32 v29, v96, v92
	v_fmac_f32_e32 v29, v53, v91
	v_fmac_f32_e32 v29, v99, v90
	ds_read_b128 v[58:61], v30 offset:13056
	ds_read_b128 v[66:69], v30 offset:8960
	ds_read_b128 v[74:77], v30 offset:4864
	ds_read_b128 v[82:85], v30 offset:768
	ds_read_b128 v[86:89], v30 offset:17152
	ds_read_b32 v90, v33 offset:20672
	s_waitcnt lgkmcnt(12)
	v_mul_f32_e32 v7, v7, v95
	v_fmac_f32_e32 v7, v96, v6
	v_fmac_f32_e32 v7, v53, v5
	v_fmac_f32_e32 v7, v99, v4
	s_waitcnt lgkmcnt(7)
	v_mul_f32_e32 v91, v55, v98
	v_mul_f32_e32 v92, v57, v98
	v_add_f32_dpp v4, v7, v7 quad_perm:[1,0,3,2] row_mask:0xf bank_mask:0xf bound_ctrl:1
	v_add_f32_dpp v5, v29, v29 quad_perm:[1,0,3,2] row_mask:0xf bank_mask:0xf bound_ctrl:1
	v_mul_f32_e32 v29, v54, v98
	v_add_f32_dpp v4, v4, v4 quad_perm:[2,3,0,1] row_mask:0xf bank_mask:0xf bound_ctrl:1
	v_add_f32_dpp v5, v5, v5 quad_perm:[2,3,0,1] row_mask:0xf bank_mask:0xf bound_ctrl:1
	v_add_u32_e32 v6, v2, v52
	v_add_f32_dpp v4, v4, v4 row_half_mirror row_mask:0xf bank_mask:0xf bound_ctrl:1
	v_add_f32_dpp v5, v5, v5 row_half_mirror row_mask:0xf bank_mask:0xf bound_ctrl:1
	s_nop 0
	v_add_f32_dpp v4, v4, v4 row_mirror row_mask:0xf bank_mask:0xf bound_ctrl:1
	v_fmac_f32_e32 v91, v4, v79
	v_fmac_f32_e32 v91, v53, v63
	v_mul_f32_e32 v53, v56, v98
	v_fmac_f32_e32 v92, v4, v81
	v_fmac_f32_e32 v53, v4, v80
	v_fmac_f32_e32 v92, v95, v65
	v_fmac_f32_e32 v53, v96, v64
	v_fmac_f32_e32 v29, v4, v78
	v_mul_f32_e32 v93, v73, v92
	v_add_f32_dpp v5, v5, v5 row_mirror row_mask:0xf bank_mask:0xf bound_ctrl:1
	v_fmac_f32_e32 v93, v53, v72
	v_fmac_f32_e32 v29, v99, v62
	ds_write_b32 v6, v5 offset:21504
	v_fmac_f32_e32 v93, v91, v71
	s_nop 0
	v_fmac_f32_e32 v93, v29, v70
	ds_read_b128 v[4:7], v30 offset:13312
	ds_read_b128 v[54:57], v30 offset:9216
	ds_read_b128 v[62:65], v30 offset:5120
	ds_read_b128 v[70:73], v30 offset:1024
	ds_read_b128 v[78:81], v30 offset:17408
	ds_read_b32 v94, v33 offset:20736
	s_waitcnt lgkmcnt(12)
	v_mul_f32_e32 v61, v61, v92
	v_fmac_f32_e32 v61, v53, v60
	v_fmac_f32_e32 v61, v91, v59
	v_fmac_f32_e32 v61, v29, v58
	v_add_f32_dpp v59, v93, v93 quad_perm:[1,0,3,2] row_mask:0xf bank_mask:0xf bound_ctrl:1
	s_waitcnt lgkmcnt(7)
	v_mul_f32_e32 v93, v66, v90
	v_add_f32_dpp v58, v61, v61 quad_perm:[1,0,3,2] row_mask:0xf bank_mask:0xf bound_ctrl:1
	v_add_f32_dpp v59, v59, v59 quad_perm:[2,3,0,1] row_mask:0xf bank_mask:0xf bound_ctrl:1
	v_add_u32_e32 v60, v13, v37
	v_add_f32_dpp v58, v58, v58 quad_perm:[2,3,0,1] row_mask:0xf bank_mask:0xf bound_ctrl:1
	v_add_f32_dpp v59, v59, v59 row_half_mirror row_mask:0xf bank_mask:0xf bound_ctrl:1
	s_nop 0
	v_add_f32_dpp v58, v58, v58 row_half_mirror row_mask:0xf bank_mask:0xf bound_ctrl:1
	v_add_f32_dpp v59, v59, v59 row_mirror row_mask:0xf bank_mask:0xf bound_ctrl:1
	ds_write_b32 v60, v59 offset:21504
	v_add_f32_dpp v58, v58, v58 row_mirror row_mask:0xf bank_mask:0xf bound_ctrl:1
	v_fmac_f32_e32 v93, v58, v86
	v_fmac_f32_e32 v93, v29, v74
	v_mul_f32_e32 v29, v67, v90
	v_fmac_f32_e32 v29, v58, v87
	v_fmac_f32_e32 v29, v91, v75
	v_mul_f32_e32 v91, v68, v90
	v_fmac_f32_e32 v91, v58, v88
	v_fmac_f32_e32 v91, v53, v76
	v_mul_f32_e32 v53, v69, v90
	v_fmac_f32_e32 v53, v58, v89
	v_fmac_f32_e32 v53, v92, v77
	s_nop 0
	v_mul_f32_e32 v90, v85, v53
	v_fmac_f32_e32 v90, v91, v84
	v_fmac_f32_e32 v90, v29, v83
	v_fmac_f32_e32 v90, v93, v82
	ds_read_b128 v[58:61], v30 offset:13568
	ds_read_b128 v[66:69], v30 offset:9472
	ds_read_b128 v[74:77], v30 offset:5376
	ds_read_b128 v[82:85], v30 offset:1280
	ds_read_b128 v[86:89], v30 offset:17664
	ds_read_b32 v92, v33 offset:20800
	s_waitcnt lgkmcnt(12)
	v_mul_f32_e32 v7, v7, v53
	v_fmac_f32_e32 v7, v91, v6
	v_fmac_f32_e32 v7, v29, v5
	v_fmac_f32_e32 v7, v93, v4
	v_add_f32_dpp v5, v90, v90 quad_perm:[1,0,3,2] row_mask:0xf bank_mask:0xf bound_ctrl:1
	s_waitcnt lgkmcnt(7)
	v_mul_f32_e32 v90, v54, v94
	v_add_f32_dpp v4, v7, v7 quad_perm:[1,0,3,2] row_mask:0xf bank_mask:0xf bound_ctrl:1
	v_add_f32_dpp v5, v5, v5 quad_perm:[2,3,0,1] row_mask:0xf bank_mask:0xf bound_ctrl:1
	v_add_u32_e32 v6, v13, v38
	v_add_f32_dpp v4, v4, v4 quad_perm:[2,3,0,1] row_mask:0xf bank_mask:0xf bound_ctrl:1
	v_add_f32_dpp v5, v5, v5 row_half_mirror row_mask:0xf bank_mask:0xf bound_ctrl:1
	s_nop 0
	v_add_f32_dpp v4, v4, v4 row_half_mirror row_mask:0xf bank_mask:0xf bound_ctrl:1
	v_add_f32_dpp v5, v5, v5 row_mirror row_mask:0xf bank_mask:0xf bound_ctrl:1
	ds_write_b32 v6, v5 offset:21504
	v_add_f32_dpp v4, v4, v4 row_mirror row_mask:0xf bank_mask:0xf bound_ctrl:1
	v_fmac_f32_e32 v90, v4, v78
	v_fmac_f32_e32 v90, v93, v62
	v_mul_f32_e32 v93, v55, v94
	v_fmac_f32_e32 v93, v4, v79
	v_fmac_f32_e32 v93, v29, v63
	v_mul_f32_e32 v29, v56, v94
	v_fmac_f32_e32 v29, v4, v80
	v_fmac_f32_e32 v29, v91, v64
	v_mul_f32_e32 v91, v57, v94
	v_fmac_f32_e32 v91, v4, v81
	v_fmac_f32_e32 v91, v53, v65
	s_nop 0
	v_mul_f32_e32 v53, v73, v91
	v_fmac_f32_e32 v53, v29, v72
	v_fmac_f32_e32 v53, v93, v71
	v_fmac_f32_e32 v53, v90, v70
	ds_read_b128 v[4:7], v30 offset:13824
	ds_read_b128 v[54:57], v30 offset:9728
	ds_read_b128 v[62:65], v30 offset:5632
	ds_read_b128 v[70:73], v30 offset:1536
	ds_read_b128 v[78:81], v30 offset:17920
	ds_read_b32 v94, v33 offset:20864
	s_waitcnt lgkmcnt(12)
	v_mul_f32_e32 v61, v61, v91
	v_fmac_f32_e32 v61, v29, v60
	v_fmac_f32_e32 v61, v93, v59
	v_fmac_f32_e32 v61, v90, v58
	v_add_f32_dpp v53, v53, v53 quad_perm:[1,0,3,2] row_mask:0xf bank_mask:0xf bound_ctrl:1
	v_add_u32_e32 v59, v13, v39
	v_add_f32_dpp v58, v61, v61 quad_perm:[1,0,3,2] row_mask:0xf bank_mask:0xf bound_ctrl:1
	v_add_f32_dpp v53, v53, v53 quad_perm:[2,3,0,1] row_mask:0xf bank_mask:0xf bound_ctrl:1
	s_waitcnt lgkmcnt(7)
	v_mul_f32_e32 v95, v66, v92
	v_add_f32_dpp v58, v58, v58 quad_perm:[2,3,0,1] row_mask:0xf bank_mask:0xf bound_ctrl:1
	v_add_f32_dpp v53, v53, v53 row_half_mirror row_mask:0xf bank_mask:0xf bound_ctrl:1
	s_nop 0
	v_add_f32_dpp v58, v58, v58 row_half_mirror row_mask:0xf bank_mask:0xf bound_ctrl:1
	v_add_f32_dpp v53, v53, v53 row_mirror row_mask:0xf bank_mask:0xf bound_ctrl:1
	ds_write_b32 v59, v53 offset:21504
	s_nop 0
	v_add_f32_dpp v53, v58, v58 row_mirror row_mask:0xf bank_mask:0xf bound_ctrl:1
	v_fmac_f32_e32 v95, v53, v86
	v_fmac_f32_e32 v95, v90, v74
	v_mul_f32_e32 v90, v67, v92
	v_fmac_f32_e32 v90, v53, v87
	v_fmac_f32_e32 v90, v93, v75
	v_mul_f32_e32 v93, v68, v92
	v_fmac_f32_e32 v93, v53, v88
	v_fmac_f32_e32 v93, v29, v76
	v_mul_f32_e32 v29, v69, v92
	v_fmac_f32_e32 v29, v53, v89
	v_fmac_f32_e32 v29, v91, v77
	s_nop 0
	v_mul_f32_e32 v53, v85, v29
	v_fmac_f32_e32 v53, v93, v84
	v_fmac_f32_e32 v53, v90, v83
	v_fmac_f32_e32 v53, v95, v82
	ds_read_b128 v[58:61], v30 offset:14080
	ds_read_b128 v[66:69], v30 offset:9984
	ds_read_b128 v[74:77], v30 offset:5888
	ds_read_b128 v[82:85], v30 offset:1792
	ds_read_b128 v[86:89], v30 offset:18176
	ds_read_b32 v91, v33 offset:20928
	s_waitcnt lgkmcnt(12)
	v_mul_f32_e32 v7, v7, v29
	v_fmac_f32_e32 v7, v93, v6
	v_fmac_f32_e32 v7, v90, v5
	v_fmac_f32_e32 v7, v95, v4
	s_waitcnt lgkmcnt(7)
	v_mul_f32_e32 v92, v55, v94
	v_add_f32_dpp v5, v53, v53 quad_perm:[1,0,3,2] row_mask:0xf bank_mask:0xf bound_ctrl:1
	v_add_f32_dpp v4, v7, v7 quad_perm:[1,0,3,2] row_mask:0xf bank_mask:0xf bound_ctrl:1
	v_mul_f32_e32 v53, v54, v94
	v_add_f32_dpp v5, v5, v5 quad_perm:[2,3,0,1] row_mask:0xf bank_mask:0xf bound_ctrl:1
	v_add_f32_dpp v4, v4, v4 quad_perm:[2,3,0,1] row_mask:0xf bank_mask:0xf bound_ctrl:1
	v_add_u32_e32 v6, v13, v40
	v_add_f32_dpp v5, v5, v5 row_half_mirror row_mask:0xf bank_mask:0xf bound_ctrl:1
	v_add_f32_dpp v4, v4, v4 row_half_mirror row_mask:0xf bank_mask:0xf bound_ctrl:1
	s_nop 0
	v_add_f32_dpp v5, v5, v5 row_mirror row_mask:0xf bank_mask:0xf bound_ctrl:1
	v_add_f32_dpp v4, v4, v4 row_mirror row_mask:0xf bank_mask:0xf bound_ctrl:1
	v_fmac_f32_e32 v92, v4, v79
	v_fmac_f32_e32 v92, v90, v63
	v_mul_f32_e32 v90, v56, v94
	v_fmac_f32_e32 v90, v4, v80
	v_fmac_f32_e32 v90, v93, v64
	v_mul_f32_e32 v93, v57, v94
	v_fmac_f32_e32 v93, v4, v81
	v_fmac_f32_e32 v93, v29, v65
	v_fmac_f32_e32 v53, v4, v78
	v_mul_f32_e32 v29, v73, v93
	v_fmac_f32_e32 v53, v95, v62
	v_fmac_f32_e32 v29, v90, v72
	ds_write_b32 v6, v5 offset:21504
	v_fmac_f32_e32 v29, v92, v71
	s_nop 0
	v_fmac_f32_e32 v29, v53, v70
	ds_read_b128 v[4:7], v30 offset:14336
	ds_read_b128 v[54:57], v30 offset:10240
	ds_read_b128 v[62:65], v30 offset:6144
	ds_read_b128 v[70:73], v30 offset:2048
	ds_read_b128 v[78:81], v30 offset:18432
	ds_read_b32 v94, v33 offset:20992
	s_waitcnt lgkmcnt(12)
	v_mul_f32_e32 v61, v61, v93
	v_fmac_f32_e32 v61, v90, v60
	v_fmac_f32_e32 v61, v92, v59
	v_fmac_f32_e32 v61, v53, v58
	v_add_f32_dpp v29, v29, v29 quad_perm:[1,0,3,2] row_mask:0xf bank_mask:0xf bound_ctrl:1
	v_add_u32_e32 v59, v13, v41
	v_add_f32_dpp v58, v61, v61 quad_perm:[1,0,3,2] row_mask:0xf bank_mask:0xf bound_ctrl:1
	v_add_f32_dpp v29, v29, v29 quad_perm:[2,3,0,1] row_mask:0xf bank_mask:0xf bound_ctrl:1
	s_waitcnt lgkmcnt(7)
	v_mul_f32_e32 v95, v66, v91
	v_add_f32_dpp v58, v58, v58 quad_perm:[2,3,0,1] row_mask:0xf bank_mask:0xf bound_ctrl:1
	v_add_f32_dpp v29, v29, v29 row_half_mirror row_mask:0xf bank_mask:0xf bound_ctrl:1
	s_nop 0
	v_add_f32_dpp v58, v58, v58 row_half_mirror row_mask:0xf bank_mask:0xf bound_ctrl:1
	v_add_f32_dpp v29, v29, v29 row_mirror row_mask:0xf bank_mask:0xf bound_ctrl:1
	ds_write_b32 v59, v29 offset:21504
	s_nop 0
	v_add_f32_dpp v29, v58, v58 row_mirror row_mask:0xf bank_mask:0xf bound_ctrl:1
	v_fmac_f32_e32 v95, v29, v86
	v_fmac_f32_e32 v95, v53, v74
	v_mul_f32_e32 v53, v67, v91
	v_fmac_f32_e32 v53, v29, v87
	v_fmac_f32_e32 v53, v92, v75
	v_mul_f32_e32 v92, v68, v91
	v_fmac_f32_e32 v92, v29, v88
	v_fmac_f32_e32 v92, v90, v76
	v_mul_f32_e32 v90, v69, v91
	v_fmac_f32_e32 v90, v29, v89
	v_fmac_f32_e32 v90, v93, v77
	s_nop 0
	v_mul_f32_e32 v29, v85, v90
	v_fmac_f32_e32 v29, v92, v84
	v_fmac_f32_e32 v29, v53, v83
	v_fmac_f32_e32 v29, v95, v82
	ds_read_b128 v[58:61], v30 offset:14592
	ds_read_b128 v[66:69], v30 offset:10496
	ds_read_b128 v[74:77], v30 offset:6400
	ds_read_b128 v[82:85], v30 offset:2304
	ds_read_b128 v[86:89], v30 offset:18688
	ds_read_b32 v91, v33 offset:21056
	s_waitcnt lgkmcnt(12)
	v_mul_f32_e32 v7, v7, v90
	v_fmac_f32_e32 v7, v92, v6
	v_fmac_f32_e32 v7, v53, v5
	v_fmac_f32_e32 v7, v95, v4
	s_waitcnt lgkmcnt(7)
	v_mul_f32_e32 v93, v55, v94
	v_add_f32_dpp v5, v29, v29 quad_perm:[1,0,3,2] row_mask:0xf bank_mask:0xf bound_ctrl:1
	v_add_f32_dpp v4, v7, v7 quad_perm:[1,0,3,2] row_mask:0xf bank_mask:0xf bound_ctrl:1
	v_mul_f32_e32 v29, v54, v94
	v_add_f32_dpp v5, v5, v5 quad_perm:[2,3,0,1] row_mask:0xf bank_mask:0xf bound_ctrl:1
	v_add_f32_dpp v4, v4, v4 quad_perm:[2,3,0,1] row_mask:0xf bank_mask:0xf bound_ctrl:1
	v_add_u32_e32 v6, v13, v44
	v_add_f32_dpp v5, v5, v5 row_half_mirror row_mask:0xf bank_mask:0xf bound_ctrl:1
	v_add_f32_dpp v4, v4, v4 row_half_mirror row_mask:0xf bank_mask:0xf bound_ctrl:1
	s_nop 0
	v_add_f32_dpp v5, v5, v5 row_mirror row_mask:0xf bank_mask:0xf bound_ctrl:1
	v_add_f32_dpp v4, v4, v4 row_mirror row_mask:0xf bank_mask:0xf bound_ctrl:1
	v_fmac_f32_e32 v93, v4, v79
	v_fmac_f32_e32 v93, v53, v63
	v_mul_f32_e32 v53, v56, v94
	v_fmac_f32_e32 v53, v4, v80
	v_fmac_f32_e32 v53, v92, v64
	v_mul_f32_e32 v92, v57, v94
	v_fmac_f32_e32 v92, v4, v81
	v_fmac_f32_e32 v92, v90, v65
	v_fmac_f32_e32 v29, v4, v78
	v_mul_f32_e32 v90, v73, v92
	v_fmac_f32_e32 v29, v95, v62
	v_fmac_f32_e32 v90, v53, v72
	ds_write_b32 v6, v5 offset:21504
	v_fmac_f32_e32 v90, v93, v71
	s_nop 0
	v_fmac_f32_e32 v90, v29, v70
	ds_read_b128 v[4:7], v30 offset:14848
	ds_read_b128 v[54:57], v30 offset:10752
	ds_read_b128 v[62:65], v30 offset:6656
	ds_read_b128 v[70:73], v30 offset:2560
	ds_read_b128 v[78:81], v30 offset:18944
	ds_read_b32 v94, v33 offset:21120
	s_waitcnt lgkmcnt(12)
	v_mul_f32_e32 v61, v61, v92
	v_fmac_f32_e32 v61, v53, v60
	v_fmac_f32_e32 v61, v93, v59
	v_fmac_f32_e32 v61, v29, v58
	v_add_f32_dpp v59, v90, v90 quad_perm:[1,0,3,2] row_mask:0xf bank_mask:0xf bound_ctrl:1
	s_waitcnt lgkmcnt(7)
	v_mul_f32_e32 v90, v66, v91
	v_add_f32_dpp v58, v61, v61 quad_perm:[1,0,3,2] row_mask:0xf bank_mask:0xf bound_ctrl:1
	v_add_f32_dpp v59, v59, v59 quad_perm:[2,3,0,1] row_mask:0xf bank_mask:0xf bound_ctrl:1
	v_add_u32_e32 v60, v13, v45
	v_add_f32_dpp v58, v58, v58 quad_perm:[2,3,0,1] row_mask:0xf bank_mask:0xf bound_ctrl:1
	v_add_f32_dpp v59, v59, v59 row_half_mirror row_mask:0xf bank_mask:0xf bound_ctrl:1
	s_nop 0
	v_add_f32_dpp v58, v58, v58 row_half_mirror row_mask:0xf bank_mask:0xf bound_ctrl:1
	v_add_f32_dpp v59, v59, v59 row_mirror row_mask:0xf bank_mask:0xf bound_ctrl:1
	ds_write_b32 v60, v59 offset:21504
	v_add_f32_dpp v58, v58, v58 row_mirror row_mask:0xf bank_mask:0xf bound_ctrl:1
	v_fmac_f32_e32 v90, v58, v86
	v_fmac_f32_e32 v90, v29, v74
	v_mul_f32_e32 v29, v67, v91
	v_fmac_f32_e32 v29, v58, v87
	v_fmac_f32_e32 v29, v93, v75
	v_mul_f32_e32 v93, v68, v91
	v_fmac_f32_e32 v93, v58, v88
	v_fmac_f32_e32 v93, v53, v76
	v_mul_f32_e32 v53, v69, v91
	v_fmac_f32_e32 v53, v58, v89
	v_fmac_f32_e32 v53, v92, v77
	s_nop 0
	v_mul_f32_e32 v91, v85, v53
	v_fmac_f32_e32 v91, v93, v84
	v_fmac_f32_e32 v91, v29, v83
	v_fmac_f32_e32 v91, v90, v82
	ds_read_b128 v[58:61], v30 offset:15104
	ds_read_b128 v[66:69], v30 offset:11008
	ds_read_b128 v[74:77], v30 offset:6912
	ds_read_b128 v[82:85], v30 offset:2816
	ds_read_b128 v[86:89], v30 offset:19200
	ds_read_b32 v92, v33 offset:21184
	s_waitcnt lgkmcnt(12)
	v_mul_f32_e32 v7, v7, v53
	v_fmac_f32_e32 v7, v93, v6
	v_fmac_f32_e32 v7, v29, v5
	v_fmac_f32_e32 v7, v90, v4
	v_add_f32_dpp v5, v91, v91 quad_perm:[1,0,3,2] row_mask:0xf bank_mask:0xf bound_ctrl:1
	s_waitcnt lgkmcnt(7)
	v_mul_f32_e32 v91, v54, v94
	v_add_f32_dpp v4, v7, v7 quad_perm:[1,0,3,2] row_mask:0xf bank_mask:0xf bound_ctrl:1
	v_add_f32_dpp v5, v5, v5 quad_perm:[2,3,0,1] row_mask:0xf bank_mask:0xf bound_ctrl:1
	v_add_u32_e32 v6, v13, v46
	v_add_f32_dpp v4, v4, v4 quad_perm:[2,3,0,1] row_mask:0xf bank_mask:0xf bound_ctrl:1
	v_add_f32_dpp v5, v5, v5 row_half_mirror row_mask:0xf bank_mask:0xf bound_ctrl:1
	s_nop 0
	v_add_f32_dpp v4, v4, v4 row_half_mirror row_mask:0xf bank_mask:0xf bound_ctrl:1
	v_add_f32_dpp v5, v5, v5 row_mirror row_mask:0xf bank_mask:0xf bound_ctrl:1
	ds_write_b32 v6, v5 offset:21504
	v_add_f32_dpp v4, v4, v4 row_mirror row_mask:0xf bank_mask:0xf bound_ctrl:1
	v_fmac_f32_e32 v91, v4, v78
	v_fmac_f32_e32 v91, v90, v62
	v_mul_f32_e32 v90, v55, v94
	v_fmac_f32_e32 v90, v4, v79
	v_fmac_f32_e32 v90, v29, v63
	v_mul_f32_e32 v29, v56, v94
	v_fmac_f32_e32 v29, v4, v80
	v_fmac_f32_e32 v29, v93, v64
	v_mul_f32_e32 v93, v57, v94
	v_fmac_f32_e32 v93, v4, v81
	v_fmac_f32_e32 v93, v53, v65
	s_nop 0
	v_mul_f32_e32 v53, v73, v93
	v_fmac_f32_e32 v53, v29, v72
	v_fmac_f32_e32 v53, v90, v71
	v_fmac_f32_e32 v53, v91, v70
	ds_read_b128 v[4:7], v30 offset:15360
	ds_read_b128 v[54:57], v30 offset:11264
	ds_read_b128 v[62:65], v30 offset:7168
	ds_read_b128 v[70:73], v30 offset:3072
	ds_read_b128 v[78:81], v30 offset:19456
	ds_read_b32 v94, v33 offset:21248
	s_waitcnt lgkmcnt(12)
	v_mul_f32_e32 v61, v61, v93
	v_fmac_f32_e32 v61, v29, v60
	v_fmac_f32_e32 v61, v90, v59
	v_fmac_f32_e32 v61, v91, v58
	v_add_f32_dpp v53, v53, v53 quad_perm:[1,0,3,2] row_mask:0xf bank_mask:0xf bound_ctrl:1
	v_add_u32_e32 v59, v13, v47
	v_add_f32_dpp v58, v61, v61 quad_perm:[1,0,3,2] row_mask:0xf bank_mask:0xf bound_ctrl:1
	v_add_f32_dpp v53, v53, v53 quad_perm:[2,3,0,1] row_mask:0xf bank_mask:0xf bound_ctrl:1
	s_waitcnt lgkmcnt(7)
	v_mul_f32_e32 v95, v66, v92
	v_add_f32_dpp v58, v58, v58 quad_perm:[2,3,0,1] row_mask:0xf bank_mask:0xf bound_ctrl:1
	v_add_f32_dpp v53, v53, v53 row_half_mirror row_mask:0xf bank_mask:0xf bound_ctrl:1
	s_nop 0
	v_add_f32_dpp v58, v58, v58 row_half_mirror row_mask:0xf bank_mask:0xf bound_ctrl:1
	v_add_f32_dpp v53, v53, v53 row_mirror row_mask:0xf bank_mask:0xf bound_ctrl:1
	ds_write_b32 v59, v53 offset:21504
	s_nop 0
	v_add_f32_dpp v53, v58, v58 row_mirror row_mask:0xf bank_mask:0xf bound_ctrl:1
	v_fmac_f32_e32 v95, v53, v86
	v_fmac_f32_e32 v95, v91, v74
	v_mul_f32_e32 v91, v67, v92
	v_fmac_f32_e32 v91, v53, v87
	v_fmac_f32_e32 v91, v90, v75
	v_mul_f32_e32 v90, v68, v92
	v_fmac_f32_e32 v90, v53, v88
	v_fmac_f32_e32 v90, v29, v76
	v_mul_f32_e32 v29, v69, v92
	v_fmac_f32_e32 v29, v53, v89
	v_fmac_f32_e32 v29, v93, v77
	s_nop 0
	v_mul_f32_e32 v53, v85, v29
	v_fmac_f32_e32 v53, v90, v84
	v_fmac_f32_e32 v53, v91, v83
	v_fmac_f32_e32 v53, v95, v82
	ds_read_b128 v[58:61], v30 offset:15616
	ds_read_b128 v[66:69], v30 offset:11520
	ds_read_b128 v[74:77], v30 offset:7424
	ds_read_b128 v[82:85], v30 offset:3328
	ds_read_b128 v[86:89], v30 offset:19712
	ds_read_b32 v92, v33 offset:21312
	s_waitcnt lgkmcnt(12)
	v_mul_f32_e32 v7, v7, v29
	v_fmac_f32_e32 v7, v90, v6
	v_fmac_f32_e32 v7, v91, v5
	v_fmac_f32_e32 v7, v95, v4
	s_waitcnt lgkmcnt(7)
	v_mul_f32_e32 v93, v55, v94
	v_add_f32_dpp v5, v53, v53 quad_perm:[1,0,3,2] row_mask:0xf bank_mask:0xf bound_ctrl:1
	v_add_f32_dpp v4, v7, v7 quad_perm:[1,0,3,2] row_mask:0xf bank_mask:0xf bound_ctrl:1
	v_mul_f32_e32 v53, v54, v94
	v_add_f32_dpp v5, v5, v5 quad_perm:[2,3,0,1] row_mask:0xf bank_mask:0xf bound_ctrl:1
	v_add_f32_dpp v4, v4, v4 quad_perm:[2,3,0,1] row_mask:0xf bank_mask:0xf bound_ctrl:1
	v_add_u32_e32 v6, v13, v48
	v_add_f32_dpp v5, v5, v5 row_half_mirror row_mask:0xf bank_mask:0xf bound_ctrl:1
	v_add_f32_dpp v4, v4, v4 row_half_mirror row_mask:0xf bank_mask:0xf bound_ctrl:1
	s_nop 0
	v_add_f32_dpp v5, v5, v5 row_mirror row_mask:0xf bank_mask:0xf bound_ctrl:1
	v_add_f32_dpp v4, v4, v4 row_mirror row_mask:0xf bank_mask:0xf bound_ctrl:1
	v_fmac_f32_e32 v93, v4, v79
	v_fmac_f32_e32 v93, v91, v63
	v_mul_f32_e32 v91, v56, v94
	v_fmac_f32_e32 v91, v4, v80
	v_fmac_f32_e32 v91, v90, v64
	v_mul_f32_e32 v90, v57, v94
	v_fmac_f32_e32 v90, v4, v81
	v_fmac_f32_e32 v90, v29, v65
	v_fmac_f32_e32 v53, v4, v78
	v_mul_f32_e32 v29, v73, v90
	v_fmac_f32_e32 v53, v95, v62
	v_fmac_f32_e32 v29, v91, v72
	ds_write_b32 v6, v5 offset:21504
	v_fmac_f32_e32 v29, v93, v71
	s_nop 0
	v_fmac_f32_e32 v29, v53, v70
	ds_read_b128 v[4:7], v30 offset:15872
	ds_read_b128 v[54:57], v30 offset:11776
	ds_read_b128 v[62:65], v30 offset:7680
	ds_read_b128 v[70:73], v30 offset:3584
	ds_read_b128 v[78:81], v30 offset:19968
	ds_read_b32 v94, v33 offset:21376
	s_waitcnt lgkmcnt(12)
	v_mul_f32_e32 v61, v61, v90
	v_fmac_f32_e32 v61, v91, v60
	v_fmac_f32_e32 v61, v93, v59
	v_fmac_f32_e32 v61, v53, v58
	v_add_f32_dpp v29, v29, v29 quad_perm:[1,0,3,2] row_mask:0xf bank_mask:0xf bound_ctrl:1
	v_add_u32_e32 v59, v13, v49
	v_add_f32_dpp v58, v61, v61 quad_perm:[1,0,3,2] row_mask:0xf bank_mask:0xf bound_ctrl:1
	v_add_f32_dpp v29, v29, v29 quad_perm:[2,3,0,1] row_mask:0xf bank_mask:0xf bound_ctrl:1
	s_waitcnt lgkmcnt(7)
	v_mul_f32_e32 v95, v66, v92
	v_add_f32_dpp v58, v58, v58 quad_perm:[2,3,0,1] row_mask:0xf bank_mask:0xf bound_ctrl:1
	v_add_f32_dpp v29, v29, v29 row_half_mirror row_mask:0xf bank_mask:0xf bound_ctrl:1
	s_nop 0
	v_add_f32_dpp v58, v58, v58 row_half_mirror row_mask:0xf bank_mask:0xf bound_ctrl:1
	v_add_f32_dpp v29, v29, v29 row_mirror row_mask:0xf bank_mask:0xf bound_ctrl:1
	ds_write_b32 v59, v29 offset:21504
	s_nop 0
	v_add_f32_dpp v29, v58, v58 row_mirror row_mask:0xf bank_mask:0xf bound_ctrl:1
	v_fmac_f32_e32 v95, v29, v86
	v_fmac_f32_e32 v95, v53, v74
	v_mul_f32_e32 v53, v67, v92
	v_fmac_f32_e32 v53, v29, v87
	v_fmac_f32_e32 v53, v93, v75
	v_mul_f32_e32 v93, v68, v92
	v_fmac_f32_e32 v93, v29, v88
	v_fmac_f32_e32 v93, v91, v76
	v_mul_f32_e32 v91, v69, v92
	v_fmac_f32_e32 v91, v29, v89
	v_fmac_f32_e32 v91, v90, v77
	s_nop 0
	v_mul_f32_e32 v29, v85, v91
	v_fmac_f32_e32 v29, v93, v84
	v_fmac_f32_e32 v29, v53, v83
	v_fmac_f32_e32 v29, v95, v82
	ds_read_b128 v[58:61], v30 offset:16128
	ds_read_b128 v[66:69], v30 offset:12032
	ds_read_b128 v[74:77], v30 offset:7936
	ds_read_b128 v[82:85], v30 offset:3840
	ds_read_b128 v[86:89], v30 offset:20224
	ds_read_b32 v90, v33 offset:21440
	s_waitcnt lgkmcnt(12)
	v_mul_f32_e32 v7, v7, v91
	v_fmac_f32_e32 v7, v93, v6
	v_fmac_f32_e32 v7, v53, v5
	v_fmac_f32_e32 v7, v95, v4
	v_add_f32_dpp v5, v29, v29 quad_perm:[1,0,3,2] row_mask:0xf bank_mask:0xf bound_ctrl:1
	s_waitcnt lgkmcnt(7)
	v_mul_f32_e32 v29, v57, v94
	v_add_f32_dpp v4, v7, v7 quad_perm:[1,0,3,2] row_mask:0xf bank_mask:0xf bound_ctrl:1
	v_add_f32_dpp v5, v5, v5 quad_perm:[2,3,0,1] row_mask:0xf bank_mask:0xf bound_ctrl:1
	v_add_u32_e32 v6, v13, v50
	v_add_f32_dpp v4, v4, v4 quad_perm:[2,3,0,1] row_mask:0xf bank_mask:0xf bound_ctrl:1
	v_add_f32_dpp v5, v5, v5 row_half_mirror row_mask:0xf bank_mask:0xf bound_ctrl:1
	v_mul_f32_e32 v7, v56, v94
	v_add_f32_dpp v4, v4, v4 row_half_mirror row_mask:0xf bank_mask:0xf bound_ctrl:1
	v_add_f32_dpp v5, v5, v5 row_mirror row_mask:0xf bank_mask:0xf bound_ctrl:1
	ds_write_b32 v6, v5 offset:21504
	v_add_f32_dpp v4, v4, v4 row_mirror row_mask:0xf bank_mask:0xf bound_ctrl:1
	v_fmac_f32_e32 v29, v4, v81
	v_mul_f32_e32 v5, v54, v94
	v_mul_f32_e32 v6, v55, v94
	v_fmac_f32_e32 v7, v4, v80
	v_fmac_f32_e32 v29, v91, v65
	v_fmac_f32_e32 v5, v4, v78
	v_fmac_f32_e32 v6, v4, v79
	v_fmac_f32_e32 v7, v93, v64
	v_fmac_f32_e32 v6, v53, v63
	v_mul_f32_e32 v4, v73, v29
	v_fmac_f32_e32 v5, v95, v62
	v_fmac_f32_e32 v4, v7, v72
	s_nop 0
	v_fmac_f32_e32 v4, v6, v71
	v_fmac_f32_e32 v4, v5, v70
	s_waitcnt lgkmcnt(6)
	v_mul_f32_e32 v53, v61, v29
	v_fmac_f32_e32 v53, v7, v60
	v_fmac_f32_e32 v53, v6, v59
	v_fmac_f32_e32 v53, v5, v58
	v_add_f32_dpp v4, v4, v4 quad_perm:[1,0,3,2] row_mask:0xf bank_mask:0xf bound_ctrl:1
	v_add_u32_e32 v13, v13, v51
	v_add_f32_dpp v53, v53, v53 quad_perm:[1,0,3,2] row_mask:0xf bank_mask:0xf bound_ctrl:1
	v_add_f32_dpp v4, v4, v4 quad_perm:[2,3,0,1] row_mask:0xf bank_mask:0xf bound_ctrl:1
	s_nop 0
	v_add_f32_dpp v53, v53, v53 quad_perm:[2,3,0,1] row_mask:0xf bank_mask:0xf bound_ctrl:1
	v_add_f32_dpp v4, v4, v4 row_half_mirror row_mask:0xf bank_mask:0xf bound_ctrl:1
	s_nop 0
	v_add_f32_dpp v53, v53, v53 row_half_mirror row_mask:0xf bank_mask:0xf bound_ctrl:1
	v_add_f32_dpp v4, v4, v4 row_mirror row_mask:0xf bank_mask:0xf bound_ctrl:1
	ds_write_b32 v13, v4 offset:21504
	v_add_f32_dpp v13, v53, v53 row_mirror row_mask:0xf bank_mask:0xf bound_ctrl:1
	s_waitcnt lgkmcnt(2)
	v_mul_f32_e32 v4, v66, v90
	v_fmac_f32_e32 v4, v13, v86
	v_fmac_f32_e32 v4, v5, v74
	v_mul_f32_e32 v5, v67, v90
	v_fmac_f32_e32 v5, v13, v87
	v_fmac_f32_e32 v5, v6, v75
	v_mul_f32_e32 v6, v68, v90
	v_fmac_f32_e32 v6, v13, v88
	v_fmac_f32_e32 v6, v7, v76
	v_mul_f32_e32 v7, v69, v90
	v_fmac_f32_e32 v7, v13, v89
	v_fmac_f32_e32 v7, v29, v77
	s_nop 0
	v_mul_f32_e32 v13, v85, v7
	v_fmac_f32_e32 v13, v6, v84
	v_fmac_f32_e32 v13, v5, v83
	v_fmac_f32_e32 v13, v4, v82
	s_nop 1
	v_add_f32_dpp v13, v13, v13 quad_perm:[1,0,3,2] row_mask:0xf bank_mask:0xf bound_ctrl:1
	s_nop 1
	v_add_f32_dpp v13, v13, v13 quad_perm:[2,3,0,1] row_mask:0xf bank_mask:0xf bound_ctrl:1
	s_nop 1
	v_add_f32_dpp v13, v13, v13 row_half_mirror row_mask:0xf bank_mask:0xf bound_ctrl:1
	s_nop 1
	v_add_f32_dpp v13, v13, v13 row_mirror row_mask:0xf bank_mask:0xf bound_ctrl:1
	ds_write_b32 v2, v13 offset:21504
	s_addk_i32 s8, 0x100
	s_add_i32 s3, s3, 1
	s_cmp_lg_u32 s9, s8
	v_add_u32_e32 v28, 16, v28
	s_waitcnt lgkmcnt(0)
	s_cbranch_scc0 .Lrw0_exitb
.LBB0_391:
	v_add_u32_e32 v31, s76, v31
	v_add_u32_e32 v32, s76, v32
	s_waitcnt vmcnt(2)
	v_and_b32_e32 v55, 0xffff0000, v16
	v_lshlrev_b32_e32 v54, 16, v16
	v_and_b32_e32 v57, 0xffff0000, v17
	v_lshlrev_b32_e32 v56, 16, v17
	s_waitcnt vmcnt(3)
	v_lshlrev_b32_e32 v2, 16, v14
	ds_write_b128 v31, v[54:57]
	s_waitcnt vmcnt(1)
	v_and_b32_e32 v55, 0xffff0000, v20
	v_lshlrev_b32_e32 v54, 16, v20
	v_and_b32_e32 v57, 0xffff0000, v21
	v_lshlrev_b32_e32 v56, 16, v21
	v_mul_f32_e32 v2, 0x3fb8aa3b, v2
	ds_write_b128 v31, v[54:57] offset:8192
	v_exp_f32_e32 v54, v2
	v_and_b32_e32 v2, 0xffff0000, v14
	v_mul_f32_e32 v2, 0x3fb8aa3b, v2
	v_exp_f32_e32 v55, v2
	v_lshlrev_b32_e32 v2, 16, v15
	v_mul_f32_e32 v2, 0x3fb8aa3b, v2
	v_exp_f32_e32 v56, v2
	v_and_b32_e32 v2, 0xffff0000, v15
	v_mul_f32_e32 v2, 0x3fb8aa3b, v2
	v_exp_f32_e32 v57, v2
	s_waitcnt vmcnt(2)
	v_and_b32_e32 v2, 0xffff0000, v18
	v_lshlrev_b32_e32 v13, 16, v18
	s_and_b32 s24, s8, 0x100
	ds_write_b128 v31, v[54:57] offset:4096
	v_xor_b32_e32 v55, 0x80000000, v2
	v_xor_b32_e32 v54, 0x80000000, v13
	v_and_b32_e32 v2, 0xffff0000, v19
	v_lshlrev_b32_e32 v13, 16, v19
	v_xor_b32_e32 v57, 0x80000000, v2
	v_xor_b32_e32 v56, 0x80000000, v13
	v_ashrrev_i32_e32 v29, 31, v28
	ds_write_b128 v31, v[54:57] offset:12288
	s_waitcnt vmcnt(1)
	v_and_b32_e32 v55, 0xffff0000, v22
	v_lshlrev_b32_e32 v54, 16, v22
	v_and_b32_e32 v57, 0xffff0000, v23
	v_lshlrev_b32_e32 v56, 16, v23
	s_waitcnt vmcnt(0)
	v_lshlrev_b32_e32 v2, 16, v27
	s_cmp_eq_u32 s8, 0
	ds_write_b128 v31, v[54:57] offset:16384
	ds_write_b32 v32, v2 offset:20480
	s_waitcnt lgkmcnt(0)
	s_barrier
	v_add_u32_e32 v30, s76, v30
	v_add_u32_e32 v33, s76, v33
	s_mul_i32 s76, s76, -1
	v_add_u32_e32 v2, 0x5000, v33
	ds_read2_b32 v[94:95], v2 offset1:16
	ds_read_b128 v[54:57], v30 offset:12288
	ds_read_b128 v[58:61], v30 offset:12544
	ds_read_b128 v[62:65], v30 offset:4096
	ds_read_b128 v[66:69], v30 offset:4352
	ds_read_b128 v[70:73], v30 offset:16384
	ds_read_b128 v[74:77], v30 offset:16640
	ds_read_b128 v[78:81], v30 offset:8192
	ds_read_b128 v[82:85], v30 offset:8448
	ds_read_b128 v[86:89], v30
	ds_read_b128 v[90:93], v30 offset:256
	s_cbranch_scc1 .LBB0_393
	s_xor_b32 s12, s24, 0x100
	v_lshl_add_u32 v2, s12, 2, v35
	ds_read_b32 v2, v2 offset:21504
	v_lshlrev_b64 v[122:123], 10, v[28:29]
	s_lshl_b32 s12, s7, 1
	v_lshl_add_u64 v[122:123], s[86:87], 0, v[122:123]
	v_lshl_add_u64 v[122:123], v[122:123], 0, s[12:13]
	s_waitcnt lgkmcnt(0)
	v_cvt_pk_bf16_f32 v13, v2, s0
	v_lshlrev_b32_e32 v2, 1, v10
	v_lshl_add_u64 v[122:123], v[122:123], 0, v[2:3]
	s_lshl_b32 s12, s2, 1
	v_lshl_add_u64 v[122:123], v[122:123], 0, s[12:13]
	v_add_co_u32_e32 v122, vcc, 0xffffc000, v122
	s_nop 1
	v_addc_co_u32_e32 v123, vcc, -1, v123, vcc
	global_store_short v[122:123], v13, off
.LBB0_393:
	s_cmp_ge_u32 s3, s6
	s_cbranch_scc1 .LBB0_390
	v_lshl_add_u64 v[14:15], v[28:29], 0, 16
	v_mov_b64_e32 v[16:17], s[46:47]
	v_mad_u64_u32 v[16:17], s[26:27], v14, s56, v[16:17]
	v_mad_i32_i24 v17, v15, s56, v17
	s_lshl_b32 s12, s2, 1
	v_lshl_add_u64 v[18:19], v[16:17], 0, s[12:13]
	v_mov_b32_e32 v13, v3
	v_lshl_add_u64 v[20:21], v[18:19], 0, v[12:13]
	v_mad_u64_u32 v[22:23], s[26:27], v14, s58, v[24:25]
	v_add_co_u32_e32 v122, vcc, s57, v20
	v_mad_i32_i24 v23, v15, s58, v23
	v_mov_b32_e32 v27, v3
	v_addc_co_u32_e32 v123, vcc, 0, v21, vcc
	global_load_dwordx2 v[14:15], v[22:23], off
	global_load_dwordx2 v[18:19], v[22:23], off offset:1024
	s_nop 0
	global_load_dwordx2 v[22:23], v[22:23], off offset:2048
	v_lshl_add_u64 v[124:125], v[16:17], 0, v[26:27]
	global_load_dwordx2 v[16:17], v[20:21], off offset:1024
	s_nop 0
	global_load_dwordx2 v[20:21], v[122:123], off offset:1024
	global_load_ushort v27, v[124:125], off
	s_branch .LBB0_390

.LBB0_1049:
	v_lshl_add_u32 v41, s54, 2, v44
	s_waitcnt lgkmcnt(4)
	v_sub_f32_e32 v52, v52, v92
	v_fma_f32 v94, v52, v60, v92
	v_sub_f32_e32 v52, v54, v92
	v_fma_f32 v95, v52, v61, v92
	v_sub_f32_e32 v52, v56, v92
	v_fma_f32 v96, v52, v62, v92
	v_sub_f32_e32 v52, v58, v92
	v_fma_f32 v97, v52, v63, v92
	v_sub_f32_e32 v52, v57, v92
	v_fma_f32 v98, v52, v64, v92
	v_sub_f32_e32 v52, v55, v92
	v_sub_f32_e32 v51, v51, v92
	v_fma_f32 v99, v52, v65, v92
	v_sub_f32_e32 v52, v53, v92
	v_fma_f32 v51, v51, v67, v92
	v_fma_f32 v100, v52, v66, v92
	v_mul_f32_e32 v52, v71, v97
	v_mul_f32_e32 v53, v75, v51
	s_nop 0
	v_fmac_f32_e32 v52, v96, v70
	v_fmac_f32_e32 v53, v100, v74
	v_fmac_f32_e32 v52, v95, v69
	v_fmac_f32_e32 v53, v99, v73
	v_fmac_f32_e32 v52, v94, v68
	v_fmac_f32_e32 v53, v98, v72
	v_add_f32_e32 v92, v52, v53
	ds_read_b128 v[52:55], v21 offset:9216
	ds_read_b128 v[56:59], v21 offset:9472
	ds_read_b128 v[60:63], v21 offset:1024
	ds_read_b128 v[64:67], v21 offset:1280
	ds_read_b32 v101, v43 offset:24704
	v_sub_f32_e32 v68, v94, v93
	s_waitcnt lgkmcnt(8)
	v_fma_f32 v94, v68, v76, v93
	v_sub_f32_e32 v68, v95, v93
	v_fma_f32 v95, v68, v77, v93
	v_sub_f32_e32 v68, v96, v93
	v_fma_f32 v96, v68, v78, v93
	v_sub_f32_e32 v68, v97, v93
	v_fma_f32 v97, v68, v79, v93
	v_sub_f32_e32 v68, v98, v93
	s_waitcnt lgkmcnt(7)
	v_fma_f32 v98, v68, v80, v93
	v_sub_f32_e32 v68, v99, v93
	v_fma_f32 v99, v68, v81, v93
	v_sub_f32_e32 v68, v100, v93
	v_sub_f32_e32 v51, v51, v93
	v_fma_f32 v100, v68, v82, v93
	v_fmac_f32_e32 v93, v51, v83
	s_waitcnt lgkmcnt(6)
	v_mul_f32_e32 v51, v87, v97
	s_waitcnt lgkmcnt(5)
	v_mul_f32_e32 v68, v91, v93
	v_fmac_f32_e32 v51, v96, v86
	v_fmac_f32_e32 v68, v100, v90
	v_fmac_f32_e32 v51, v95, v85
	v_fmac_f32_e32 v68, v99, v89
	s_nop 0
	v_fmac_f32_e32 v51, v94, v84
	v_fmac_f32_e32 v68, v98, v88
	v_add_f32_e32 v51, v51, v68
	ds_read_b128 v[68:71], v21 offset:9728
	ds_read_b128 v[72:75], v21 offset:9984
	ds_read_b128 v[76:79], v21 offset:1536
	ds_read_b128 v[80:83], v21 offset:1792
	ds_read_b32 v84, v43 offset:24768
	s_waitcnt lgkmcnt(5)
	v_sub_f32_e32 v85, v94, v101
	v_fma_f32 v85, v85, v52, v101
	v_sub_f32_e32 v52, v95, v101
	v_fma_f32 v86, v52, v53, v101
	v_sub_f32_e32 v52, v96, v101
	v_fma_f32 v87, v52, v54, v101
	v_sub_f32_e32 v52, v97, v101
	v_fma_f32 v88, v52, v55, v101
	v_sub_f32_e32 v52, v98, v101
	v_fma_f32 v89, v52, v56, v101
	v_sub_f32_e32 v52, v99, v101
	v_fma_f32 v90, v52, v57, v101
	v_sub_f32_e32 v52, v100, v101
	v_fma_f32 v91, v52, v58, v101
	v_sub_f32_e32 v52, v93, v101
	v_fmac_f32_e32 v101, v52, v59
	s_nop 0
	v_mul_f32_e32 v52, v63, v88
	v_mul_f32_e32 v53, v67, v101
	v_fmac_f32_e32 v52, v87, v62
	v_fmac_f32_e32 v53, v91, v66
	v_fmac_f32_e32 v52, v86, v61
	v_fmac_f32_e32 v53, v90, v65
	s_nop 0
	v_fmac_f32_e32 v52, v85, v60
	v_fmac_f32_e32 v53, v89, v64
	v_add_f32_e32 v93, v52, v53
	ds_read_b128 v[52:55], v21 offset:10240
	ds_read_b128 v[56:59], v21 offset:10496
	ds_read_b128 v[60:63], v21 offset:2048
	ds_read_b128 v[64:67], v21 offset:2304
	ds_read_b32 v94, v43 offset:24832
	s_waitcnt lgkmcnt(5)
	v_sub_f32_e32 v85, v85, v84
	v_fma_f32 v85, v85, v68, v84
	v_sub_f32_e32 v68, v86, v84
	v_fma_f32 v86, v68, v69, v84
	v_sub_f32_e32 v68, v87, v84
	v_fma_f32 v87, v68, v70, v84
	v_sub_f32_e32 v68, v88, v84
	v_fma_f32 v88, v68, v71, v84
	v_sub_f32_e32 v68, v89, v84
	v_fma_f32 v89, v68, v72, v84
	v_sub_f32_e32 v68, v90, v84
	v_fma_f32 v90, v68, v73, v84
	v_sub_f32_e32 v68, v91, v84
	v_fma_f32 v91, v68, v74, v84
	v_sub_f32_e32 v68, v101, v84
	v_fmac_f32_e32 v84, v68, v75
	s_nop 0
	v_mul_f32_e32 v68, v79, v88
	v_mul_f32_e32 v69, v83, v84
	v_fmac_f32_e32 v68, v87, v78
	v_fmac_f32_e32 v69, v91, v82
	v_fmac_f32_e32 v68, v86, v77
	v_fmac_f32_e32 v69, v90, v81
	s_nop 0
	v_fmac_f32_e32 v68, v85, v76
	v_fmac_f32_e32 v69, v89, v80
	v_add_f32_e32 v68, v68, v69
	v_cndmask_b32_e64 v69, v51, v92, s[0:1]
	v_cndmask_b32_e64 v51, v92, v51, s[0:1]
	v_cndmask_b32_e64 v70, v68, v93, s[0:1]
	v_cndmask_b32_e64 v68, v93, v68, s[0:1]
	v_add_f32_dpp v51, v51, v69 quad_perm:[1,0,3,2] row_mask:0xf bank_mask:0xf bound_ctrl:1
	s_nop 0
	v_add_f32_dpp v68, v68, v70 quad_perm:[1,0,3,2] row_mask:0xf bank_mask:0xf bound_ctrl:1
	v_cndmask_b32_e64 v69, v68, v51, s[4:5]
	v_cndmask_b32_e64 v51, v51, v68, s[4:5]
	s_nop 1
	v_add_f32_dpp v51, v51, v69 quad_perm:[2,3,0,1] row_mask:0xf bank_mask:0xf bound_ctrl:1
	s_nop 1
	v_add_f32_dpp v51, v51, v51 row_ror:4 row_mask:0xf bank_mask:0xf bound_ctrl:1
	s_nop 1
	v_add_f32_dpp v51, v51, v51 row_ror:8 row_mask:0xf bank_mask:0xf bound_ctrl:1
	ds_write_b32 v41, v51 offset:25600
	ds_read_b128 v[68:71], v21 offset:10752
	ds_read_b128 v[72:75], v21 offset:11008
	ds_read_b128 v[76:79], v21 offset:2560
	ds_read_b128 v[80:83], v21 offset:2816
	ds_read_b32 v51, v43 offset:24896
	s_waitcnt lgkmcnt(6)
	v_sub_f32_e32 v85, v85, v94
	v_fma_f32 v85, v85, v52, v94
	v_sub_f32_e32 v52, v86, v94
	v_fma_f32 v86, v52, v53, v94
	v_sub_f32_e32 v52, v87, v94
	v_fma_f32 v87, v52, v54, v94
	v_sub_f32_e32 v52, v88, v94
	v_fma_f32 v88, v52, v55, v94
	v_sub_f32_e32 v52, v89, v94
	v_fma_f32 v89, v52, v56, v94
	v_sub_f32_e32 v52, v90, v94
	v_fma_f32 v90, v52, v57, v94
	v_sub_f32_e32 v52, v91, v94
	v_fma_f32 v91, v52, v58, v94
	v_sub_f32_e32 v52, v84, v94
	v_fmac_f32_e32 v94, v52, v59
	s_nop 0
	v_mul_f32_e32 v52, v63, v88
	v_mul_f32_e32 v53, v67, v94
	v_fmac_f32_e32 v52, v87, v62
	v_fmac_f32_e32 v53, v91, v66
	v_fmac_f32_e32 v52, v86, v61
	v_fmac_f32_e32 v53, v90, v65
	s_nop 0
	v_fmac_f32_e32 v52, v85, v60
	v_fmac_f32_e32 v53, v89, v64
	v_add_f32_e32 v84, v52, v53
	ds_read_b128 v[52:55], v21 offset:11264
	ds_read_b128 v[56:59], v21 offset:11520
	ds_read_b128 v[60:63], v21 offset:3072
	ds_read_b128 v[64:67], v21 offset:3328
	ds_read_b32 v92, v43 offset:24960
	s_waitcnt lgkmcnt(5)
	v_sub_f32_e32 v85, v85, v51
	v_fma_f32 v85, v85, v68, v51
	v_sub_f32_e32 v68, v86, v51
	v_fma_f32 v86, v68, v69, v51
	v_sub_f32_e32 v68, v87, v51
	v_fma_f32 v87, v68, v70, v51
	v_sub_f32_e32 v68, v88, v51
	v_fma_f32 v88, v68, v71, v51
	v_sub_f32_e32 v68, v89, v51
	v_fma_f32 v89, v68, v72, v51
	v_sub_f32_e32 v68, v90, v51
	v_fma_f32 v90, v68, v73, v51
	v_sub_f32_e32 v68, v91, v51
	v_fma_f32 v91, v68, v74, v51
	v_sub_f32_e32 v68, v94, v51
	v_fmac_f32_e32 v51, v68, v75
	s_nop 0
	v_mul_f32_e32 v68, v79, v88
	v_mul_f32_e32 v69, v83, v51
	v_fmac_f32_e32 v68, v87, v78
	v_fmac_f32_e32 v69, v91, v82
	v_fmac_f32_e32 v68, v86, v77
	v_fmac_f32_e32 v69, v90, v81
	s_nop 0
	v_fmac_f32_e32 v68, v85, v76
	v_fmac_f32_e32 v69, v89, v80
	v_add_f32_e32 v93, v68, v69
	ds_read_b128 v[68:71], v21 offset:11776
	ds_read_b128 v[72:75], v21 offset:12032
	ds_read_b128 v[76:79], v21 offset:3584
	ds_read_b128 v[80:83], v21 offset:3840
	ds_read_b32 v94, v43 offset:25024
	s_waitcnt lgkmcnt(5)
	v_sub_f32_e32 v85, v85, v92
	v_fma_f32 v85, v85, v52, v92
	v_sub_f32_e32 v52, v86, v92
	v_fma_f32 v86, v52, v53, v92
	v_sub_f32_e32 v52, v87, v92
	v_fma_f32 v87, v52, v54, v92
	v_sub_f32_e32 v52, v88, v92
	v_fma_f32 v88, v52, v55, v92
	v_sub_f32_e32 v52, v89, v92
	v_fma_f32 v89, v52, v56, v92
	v_sub_f32_e32 v52, v90, v92
	v_fma_f32 v90, v52, v57, v92
	v_sub_f32_e32 v52, v91, v92
	v_sub_f32_e32 v51, v51, v92
	v_fma_f32 v91, v52, v58, v92
	v_fmac_f32_e32 v92, v51, v59
	s_nop 0
	v_mul_f32_e32 v51, v63, v88
	v_mul_f32_e32 v52, v67, v92
	v_fmac_f32_e32 v51, v87, v62
	v_fmac_f32_e32 v52, v91, v66
	v_fmac_f32_e32 v51, v86, v61
	v_fmac_f32_e32 v52, v90, v65
	s_nop 0
	v_fmac_f32_e32 v51, v85, v60
	v_fmac_f32_e32 v52, v89, v64
	v_add_f32_e32 v51, v51, v52
	ds_read_b128 v[52:55], v21 offset:12288
	ds_read_b128 v[56:59], v21 offset:12544
	ds_read_b128 v[60:63], v21 offset:4096
	ds_read_b128 v[64:67], v21 offset:4352
	ds_read_b32 v95, v43 offset:25088
	s_waitcnt lgkmcnt(5)
	v_sub_f32_e32 v85, v85, v94
	v_fma_f32 v85, v85, v68, v94
	v_sub_f32_e32 v68, v86, v94
	v_fma_f32 v86, v68, v69, v94
	v_sub_f32_e32 v68, v87, v94
	v_fma_f32 v87, v68, v70, v94
	v_sub_f32_e32 v68, v88, v94
	v_fma_f32 v88, v68, v71, v94
	v_sub_f32_e32 v68, v89, v94
	v_fma_f32 v89, v68, v72, v94
	v_sub_f32_e32 v68, v90, v94
	v_fma_f32 v90, v68, v73, v94
	v_sub_f32_e32 v68, v91, v94
	v_fma_f32 v91, v68, v74, v94
	v_sub_f32_e32 v68, v92, v94
	v_fmac_f32_e32 v94, v68, v75
	s_nop 0
	v_mul_f32_e32 v68, v79, v88
	v_mul_f32_e32 v69, v83, v94
	v_fmac_f32_e32 v68, v87, v78
	v_fmac_f32_e32 v69, v91, v82
	v_fmac_f32_e32 v68, v86, v77
	v_fmac_f32_e32 v69, v90, v81
	v_cndmask_b32_e64 v70, v84, v93, s[0:1]
	v_fmac_f32_e32 v68, v85, v76
	v_fmac_f32_e32 v69, v89, v80
	v_add_f32_e32 v68, v68, v69
	v_cndmask_b32_e64 v69, v93, v84, s[0:1]
	v_cndmask_b32_e64 v71, v68, v51, s[0:1]
	v_cndmask_b32_e64 v51, v51, v68, s[0:1]
	v_add_f32_dpp v68, v70, v69 quad_perm:[1,0,3,2] row_mask:0xf bank_mask:0xf bound_ctrl:1
	s_nop 0
	v_add_f32_dpp v51, v51, v71 quad_perm:[1,0,3,2] row_mask:0xf bank_mask:0xf bound_ctrl:1
	v_cndmask_b32_e64 v69, v51, v68, s[4:5]
	v_cndmask_b32_e64 v51, v68, v51, s[4:5]
	v_add_u32_e32 v68, v41, v46
	s_nop 0
	v_add_f32_dpp v51, v51, v69 quad_perm:[2,3,0,1] row_mask:0xf bank_mask:0xf bound_ctrl:1
	s_nop 1
	v_add_f32_dpp v51, v51, v51 row_ror:4 row_mask:0xf bank_mask:0xf bound_ctrl:1
	s_nop 1
	v_add_f32_dpp v51, v51, v51 row_ror:8 row_mask:0xf bank_mask:0xf bound_ctrl:1
	ds_write_b32 v68, v51 offset:25600
	ds_read_b128 v[68:71], v21 offset:12800
	ds_read_b128 v[72:75], v21 offset:13056
	ds_read_b128 v[76:79], v21 offset:4608
	ds_read_b128 v[80:83], v21 offset:4864
	ds_read_b32 v51, v43 offset:25152
	s_waitcnt lgkmcnt(6)
	v_sub_f32_e32 v84, v85, v95
	v_fma_f32 v84, v84, v52, v95
	v_sub_f32_e32 v52, v86, v95
	v_fma_f32 v85, v52, v53, v95
	v_sub_f32_e32 v52, v87, v95
	v_fma_f32 v86, v52, v54, v95
	v_sub_f32_e32 v52, v88, v95
	v_fma_f32 v87, v52, v55, v95
	v_sub_f32_e32 v52, v89, v95
	v_fma_f32 v88, v52, v56, v95
	v_sub_f32_e32 v52, v90, v95
	v_fma_f32 v89, v52, v57, v95
	v_sub_f32_e32 v52, v91, v95
	v_fma_f32 v90, v52, v58, v95
	v_sub_f32_e32 v52, v94, v95
	v_fmac_f32_e32 v95, v52, v59
	s_nop 0
	v_mul_f32_e32 v52, v63, v87
	v_mul_f32_e32 v53, v67, v95
	v_fmac_f32_e32 v52, v86, v62
	v_fmac_f32_e32 v53, v90, v66
	v_fmac_f32_e32 v52, v85, v61
	v_fmac_f32_e32 v53, v89, v65
	s_nop 0
	v_fmac_f32_e32 v52, v84, v60
	v_fmac_f32_e32 v53, v88, v64
	v_add_f32_e32 v91, v52, v53
	ds_read_b128 v[52:55], v21 offset:13312
	ds_read_b128 v[56:59], v21 offset:13568
	ds_read_b128 v[60:63], v21 offset:5120
	ds_read_b128 v[64:67], v21 offset:5376
	ds_read_b32 v92, v43 offset:25216
	s_waitcnt lgkmcnt(5)
	v_sub_f32_e32 v84, v84, v51
	v_fma_f32 v84, v84, v68, v51
	v_sub_f32_e32 v68, v85, v51
	v_fma_f32 v85, v68, v69, v51
	v_sub_f32_e32 v68, v86, v51
	v_fma_f32 v86, v68, v70, v51
	v_sub_f32_e32 v68, v87, v51
	v_fma_f32 v87, v68, v71, v51
	v_sub_f32_e32 v68, v88, v51
	v_fma_f32 v88, v68, v72, v51
	v_sub_f32_e32 v68, v89, v51
	v_fma_f32 v89, v68, v73, v51
	v_sub_f32_e32 v68, v90, v51
	v_fma_f32 v90, v68, v74, v51
	v_sub_f32_e32 v68, v95, v51
	v_fmac_f32_e32 v51, v68, v75
	s_nop 0
	v_mul_f32_e32 v68, v79, v87
	v_mul_f32_e32 v69, v83, v51
	v_fmac_f32_e32 v68, v86, v78
	v_fmac_f32_e32 v69, v90, v82
	v_fmac_f32_e32 v68, v85, v77
	v_fmac_f32_e32 v69, v89, v81
	s_nop 0
	v_fmac_f32_e32 v68, v84, v76
	v_fmac_f32_e32 v69, v88, v80
	v_add_f32_e32 v93, v68, v69
	ds_read_b128 v[68:71], v21 offset:13824
	ds_read_b128 v[72:75], v21 offset:14080
	ds_read_b128 v[76:79], v21 offset:5632
	ds_read_b128 v[80:83], v21 offset:5888
	ds_read_b32 v94, v43 offset:25280
	s_waitcnt lgkmcnt(5)
	v_sub_f32_e32 v84, v84, v92
	v_fma_f32 v84, v84, v52, v92
	v_sub_f32_e32 v52, v85, v92
	v_fma_f32 v85, v52, v53, v92
	v_sub_f32_e32 v52, v86, v92
	v_fma_f32 v86, v52, v54, v92
	v_sub_f32_e32 v52, v87, v92
	v_fma_f32 v87, v52, v55, v92
	v_sub_f32_e32 v52, v88, v92
	v_fma_f32 v88, v52, v56, v92
	v_sub_f32_e32 v52, v89, v92
	v_fma_f32 v89, v52, v57, v92
	v_sub_f32_e32 v52, v90, v92
	v_sub_f32_e32 v51, v51, v92
	v_fma_f32 v90, v52, v58, v92
	v_fmac_f32_e32 v92, v51, v59
	s_nop 0
	v_mul_f32_e32 v51, v63, v87
	v_mul_f32_e32 v52, v67, v92
	v_fmac_f32_e32 v51, v86, v62
	v_fmac_f32_e32 v52, v90, v66
	v_fmac_f32_e32 v51, v85, v61
	v_fmac_f32_e32 v52, v89, v65
	s_nop 0
	v_fmac_f32_e32 v51, v84, v60
	v_fmac_f32_e32 v52, v88, v64
	v_add_f32_e32 v51, v51, v52
	ds_read_b128 v[52:55], v21 offset:14336
	ds_read_b128 v[56:59], v21 offset:14592
	ds_read_b128 v[60:63], v21 offset:6144
	ds_read_b128 v[64:67], v21 offset:6400
	ds_read_b32 v95, v43 offset:25344
	s_waitcnt lgkmcnt(5)
	v_sub_f32_e32 v84, v84, v94
	v_fma_f32 v84, v84, v68, v94
	v_sub_f32_e32 v68, v85, v94
	v_fma_f32 v85, v68, v69, v94
	v_sub_f32_e32 v68, v86, v94
	v_fma_f32 v86, v68, v70, v94
	v_sub_f32_e32 v68, v87, v94
	v_fma_f32 v87, v68, v71, v94
	v_sub_f32_e32 v68, v88, v94
	v_fma_f32 v88, v68, v72, v94
	v_sub_f32_e32 v68, v89, v94
	v_fma_f32 v89, v68, v73, v94
	v_sub_f32_e32 v68, v90, v94
	v_fma_f32 v90, v68, v74, v94
	v_sub_f32_e32 v68, v92, v94
	v_fmac_f32_e32 v94, v68, v75
	s_nop 0
	v_mul_f32_e32 v68, v79, v87
	v_mul_f32_e32 v69, v83, v94
	v_fmac_f32_e32 v68, v86, v78
	v_fmac_f32_e32 v69, v90, v82
	v_fmac_f32_e32 v68, v85, v77
	v_fmac_f32_e32 v69, v89, v81
	v_cndmask_b32_e64 v70, v91, v93, s[0:1]
	v_fmac_f32_e32 v68, v84, v76
	v_fmac_f32_e32 v69, v88, v80
	v_add_f32_e32 v68, v68, v69
	v_cndmask_b32_e64 v69, v93, v91, s[0:1]
	v_cndmask_b32_e64 v71, v68, v51, s[0:1]
	v_cndmask_b32_e64 v51, v51, v68, s[0:1]
	v_add_f32_dpp v68, v70, v69 quad_perm:[1,0,3,2] row_mask:0xf bank_mask:0xf bound_ctrl:1
	s_nop 0
	v_add_f32_dpp v51, v51, v71 quad_perm:[1,0,3,2] row_mask:0xf bank_mask:0xf bound_ctrl:1
	v_cndmask_b32_e64 v69, v51, v68, s[4:5]
	v_cndmask_b32_e64 v51, v68, v51, s[4:5]
	v_add_u32_e32 v68, v41, v47
	s_nop 0
	v_add_f32_dpp v51, v51, v69 quad_perm:[2,3,0,1] row_mask:0xf bank_mask:0xf bound_ctrl:1
	s_nop 1
	v_add_f32_dpp v51, v51, v51 row_ror:4 row_mask:0xf bank_mask:0xf bound_ctrl:1
	s_nop 1
	v_add_f32_dpp v51, v51, v51 row_ror:8 row_mask:0xf bank_mask:0xf bound_ctrl:1
	ds_write_b32 v68, v51 offset:25600
	ds_read_b128 v[68:71], v21 offset:14848
	ds_read_b128 v[72:75], v21 offset:15104
	ds_read_b128 v[76:79], v21 offset:6656
	ds_read_b128 v[80:83], v21 offset:6912
	ds_read_b32 v91, v43 offset:25408
	s_waitcnt lgkmcnt(6)
	v_sub_f32_e32 v51, v84, v95
	v_fma_f32 v51, v51, v52, v95
	v_sub_f32_e32 v52, v85, v95
	v_fma_f32 v84, v52, v53, v95
	v_sub_f32_e32 v52, v86, v95
	v_fma_f32 v85, v52, v54, v95
	v_sub_f32_e32 v52, v87, v95
	v_fma_f32 v86, v52, v55, v95
	v_sub_f32_e32 v52, v88, v95
	v_fma_f32 v87, v52, v56, v95
	v_sub_f32_e32 v52, v89, v95
	v_fma_f32 v88, v52, v57, v95
	v_sub_f32_e32 v52, v90, v95
	v_fma_f32 v89, v52, v58, v95
	v_sub_f32_e32 v52, v94, v95
	v_fmac_f32_e32 v95, v52, v59
	s_nop 0
	v_mul_f32_e32 v52, v63, v86
	v_mul_f32_e32 v53, v67, v95
	v_fmac_f32_e32 v52, v85, v62
	v_fmac_f32_e32 v53, v89, v66
	v_fmac_f32_e32 v52, v84, v61
	v_fmac_f32_e32 v53, v88, v65
	s_nop 0
	v_fmac_f32_e32 v52, v51, v60
	v_fmac_f32_e32 v53, v87, v64
	v_add_f32_e32 v90, v52, v53
	ds_read_b128 v[52:55], v21 offset:15360
	ds_read_b128 v[56:59], v21 offset:15616
	ds_read_b128 v[60:63], v21 offset:7168
	ds_read_b128 v[64:67], v21 offset:7424
	ds_read_b32 v92, v43 offset:25472
	s_waitcnt lgkmcnt(5)
	v_sub_f32_e32 v51, v51, v91
	v_fma_f32 v93, v51, v68, v91
	v_sub_f32_e32 v51, v84, v91
	v_fma_f32 v84, v51, v69, v91
	v_sub_f32_e32 v51, v85, v91
	v_fma_f32 v85, v51, v70, v91
	v_sub_f32_e32 v51, v86, v91
	v_fma_f32 v86, v51, v71, v91
	v_sub_f32_e32 v51, v87, v91
	v_fma_f32 v87, v51, v72, v91
	v_sub_f32_e32 v51, v88, v91
	v_fma_f32 v88, v51, v73, v91
	v_sub_f32_e32 v51, v89, v91
	v_fma_f32 v89, v51, v74, v91
	v_sub_f32_e32 v51, v95, v91
	v_fmac_f32_e32 v91, v51, v75
	s_nop 0
	v_mul_f32_e32 v51, v79, v86
	v_mul_f32_e32 v68, v83, v91
	v_fmac_f32_e32 v51, v85, v78
	v_fmac_f32_e32 v68, v89, v82
	v_fmac_f32_e32 v51, v84, v77
	v_fmac_f32_e32 v68, v88, v81
	s_nop 0
	v_fmac_f32_e32 v51, v93, v76
	v_fmac_f32_e32 v68, v87, v80
	v_add_f32_e32 v94, v51, v68
	ds_read_b128 v[68:71], v21 offset:15872
	ds_read_b128 v[72:75], v21 offset:16128
	ds_read_b128 v[76:79], v21 offset:7680
	ds_read_b128 v[80:83], v21 offset:7936
	ds_read_b32 v51, v43 offset:25536
	s_waitcnt lgkmcnt(5)
	v_sub_f32_e32 v84, v84, v92
	v_fma_f32 v53, v84, v53, v92
	v_sub_f32_e32 v84, v85, v92
	v_fma_f32 v84, v84, v54, v92
	v_sub_f32_e32 v54, v86, v92
	v_fma_f32 v55, v54, v55, v92
	v_sub_f32_e32 v54, v87, v92
	v_fma_f32 v85, v54, v56, v92
	v_sub_f32_e32 v54, v88, v92
	v_fma_f32 v86, v54, v57, v92
	v_sub_f32_e32 v54, v89, v92
	v_sub_f32_e32 v93, v93, v92
	v_fma_f32 v87, v54, v58, v92
	v_sub_f32_e32 v54, v91, v92
	v_fma_f32 v52, v93, v52, v92
	v_fmac_f32_e32 v92, v54, v59
	s_nop 0
	v_mul_f32_e32 v54, v63, v55
	v_mul_f32_e32 v56, v67, v92
	v_fmac_f32_e32 v54, v84, v62
	v_fmac_f32_e32 v56, v87, v66
	v_fmac_f32_e32 v54, v53, v61
	v_fmac_f32_e32 v56, v86, v65
	s_nop 0
	v_fmac_f32_e32 v54, v52, v60
	v_fmac_f32_e32 v56, v85, v64
	v_add_f32_e32 v59, v54, v56
	s_waitcnt lgkmcnt(0)
	v_sub_f32_e32 v53, v53, v51
	v_fma_f32 v54, v53, v69, v51
	v_sub_f32_e32 v53, v84, v51
	v_fma_f32 v56, v53, v70, v51
	v_sub_f32_e32 v53, v55, v51
	v_fma_f32 v58, v53, v71, v51
	v_sub_f32_e32 v53, v85, v51
	v_fma_f32 v57, v53, v72, v51
	v_sub_f32_e32 v53, v86, v51
	v_sub_f32_e32 v52, v52, v51
	v_fma_f32 v55, v53, v73, v51
	v_sub_f32_e32 v53, v87, v51
	v_sub_f32_e32 v60, v92, v51
	v_fma_f32 v52, v52, v68, v51
	v_fma_f32 v53, v53, v74, v51
	v_fmac_f32_e32 v51, v60, v75
	s_nop 0
	v_mul_f32_e32 v60, v79, v58
	v_mul_f32_e32 v61, v83, v51
	v_fmac_f32_e32 v60, v56, v78
	v_fmac_f32_e32 v61, v53, v82
	v_fmac_f32_e32 v60, v54, v77
	v_fmac_f32_e32 v61, v55, v81
	v_cndmask_b32_e64 v62, v90, v94, s[0:1]
	v_fmac_f32_e32 v60, v52, v76
	v_fmac_f32_e32 v61, v57, v80
	v_add_f32_e32 v60, v60, v61
	v_cndmask_b32_e64 v61, v94, v90, s[0:1]
	v_cndmask_b32_e64 v63, v60, v59, s[0:1]
	v_cndmask_b32_e64 v59, v59, v60, s[0:1]
	v_add_f32_dpp v60, v62, v61 quad_perm:[1,0,3,2] row_mask:0xf bank_mask:0xf bound_ctrl:1
	v_add_u32_e32 v41, v41, v48
	v_add_f32_dpp v59, v59, v63 quad_perm:[1,0,3,2] row_mask:0xf bank_mask:0xf bound_ctrl:1
	v_cndmask_b32_e64 v61, v59, v60, s[4:5]
	v_cndmask_b32_e64 v59, v60, v59, s[4:5]
	s_nop 1
	v_add_f32_dpp v59, v59, v61 quad_perm:[2,3,0,1] row_mask:0xf bank_mask:0xf bound_ctrl:1
	s_nop 1
	v_add_f32_dpp v59, v59, v59 row_ror:4 row_mask:0xf bank_mask:0xf bound_ctrl:1
	s_nop 1
	v_add_f32_dpp v59, v59, v59 row_ror:8 row_mask:0xf bank_mask:0xf bound_ctrl:1
	ds_write_b32 v41, v59 offset:25600
	s_addk_i32 s31, 0x100
	s_add_i32 s30, s30, 1
	s_cmp_lg_u32 s53, s31
	v_add_u32_e32 v50, 16, v50
	s_waitcnt lgkmcnt(0)
	s_cbranch_scc0 .Lhg1_exitb
.LBB0_1050:
	v_add_u32_e32 v15, s77, v15
	v_add_u32_e32 v17, s78, v17
	s_waitcnt vmcnt(0)
	v_lshlrev_b32_e32 v41, 16, v8
	v_mul_f32_e32 v41, 0xbfb8aa3b, v41
	v_and_b32_e32 v59, 0xffff0000, v8
	v_exp_f32_e32 v41, v41
	v_mul_f32_e32 v59, 0xbfb8aa3b, v59
	v_exp_f32_e32 v59, v59
	v_lshlrev_b32_e32 v60, 16, v4
	v_add_f32_e32 v41, 1.0, v41
	v_rcp_f32_e32 v68, v41
	v_add_f32_e32 v41, 1.0, v59
	v_rcp_f32_e32 v69, v41
	v_lshlrev_b32_e32 v41, 16, v9
	v_mul_f32_e32 v41, 0xbfb8aa3b, v41
	v_and_b32_e32 v59, 0xffff0000, v9
	v_exp_f32_e32 v41, v41
	v_mul_f32_e32 v59, 0xbfb8aa3b, v59
	v_exp_f32_e32 v59, v59
	v_and_b32_e32 v61, 0xffff0000, v4
	v_add_f32_e32 v41, 1.0, v41
	v_rcp_f32_e32 v70, v41
	v_add_f32_e32 v41, 1.0, v59
	v_rcp_f32_e32 v71, v41
	v_lshlrev_b32_e32 v41, 16, v10
	v_mul_f32_e32 v41, 0xbfb8aa3b, v41
	v_and_b32_e32 v59, 0xffff0000, v10
	v_exp_f32_e32 v41, v41
	v_mul_f32_e32 v59, 0xbfb8aa3b, v59
	v_exp_f32_e32 v59, v59
	v_lshlrev_b32_e32 v62, 16, v5
	v_add_f32_e32 v41, 1.0, v41
	v_rcp_f32_e32 v72, v41
	v_add_f32_e32 v41, 1.0, v59
	v_rcp_f32_e32 v73, v41
	v_lshlrev_b32_e32 v41, 16, v11
	v_mul_f32_e32 v41, 0xbfb8aa3b, v41
	v_and_b32_e32 v59, 0xffff0000, v11
	v_exp_f32_e32 v41, v41
	v_mul_f32_e32 v59, 0xbfb8aa3b, v59
	v_exp_f32_e32 v59, v59
	v_and_b32_e32 v63, 0xffff0000, v5
	v_add_f32_e32 v41, 1.0, v41
	v_rcp_f32_e32 v74, v41
	v_add_f32_e32 v41, 1.0, v59
	v_rcp_f32_e32 v75, v41
	v_lshlrev_b32_e32 v64, 16, v6
	v_and_b32_e32 v65, 0xffff0000, v6
	v_lshlrev_b32_e32 v66, 16, v7
	v_and_b32_e32 v67, 0xffff0000, v7
	s_and_b32 s54, s31, 0x100
	ds_write_b128 v15, v[60:63]
	ds_write_b128 v15, v[64:67] offset:16
	v_pk_fma_f32 v[60:61], v[30:31], v[68:69], v[22:23]
	v_pk_fma_f32 v[62:63], v[32:33], v[70:71], v[24:25]
	ds_write_b128 v15, v[60:63] offset:8192
	v_pk_fma_f32 v[60:61], v[34:35], v[72:73], v[26:27]
	v_pk_fma_f32 v[62:63], v[36:37], v[74:75], v[28:29]
	v_lshlrev_b32_e32 v41, 16, v39
	s_cmp_eq_u32 s31, 0
	ds_write_b128 v15, v[60:63] offset:8208
	ds_write_b32 v17, v41 offset:24576
	s_waitcnt lgkmcnt(0)
	s_barrier
	v_add_u32_e32 v21, s77, v21
	v_add_u32_e32 v43, s78, v43
	v_add_u32_e32 v49, s78, v49
	s_mul_i32 s77, s77, -1
	s_mul_i32 s78, s78, -1
	ds_read_b128 v[60:63], v21 offset:8192
	ds_read_b128 v[64:67], v21 offset:8448
	ds_read_b128 v[68:71], v21
	ds_read_b128 v[72:75], v21 offset:256
	ds_read2_b32 v[92:93], v49 offset1:16
	ds_read_b128 v[76:79], v21 offset:8704
	ds_read_b128 v[80:83], v21 offset:8960
	ds_read_b128 v[84:87], v21 offset:512
	ds_read_b128 v[88:91], v21 offset:768
	s_cbranch_scc1 .LBB0_1052
	v_mov_b64_e32 v[122:123], s[46:47]
	v_mad_i64_i32 v[122:123], s[56:57], v50, s50, v[122:123]
	s_lshl_b32 s14, s29, 1
	v_lshl_add_u64 v[122:123], v[122:123], 0, s[14:15]
	s_lshl_b32 s14, s27, 1
	v_lshl_add_u64 v[122:123], v[122:123], 0, s[14:15]
	s_xor_b32 s14, s54, 0x100
	v_lshl_add_u32 v41, s14, 2, v45
	ds_read_b32 v41, v41 offset:25600
	v_lshl_add_u64 v[122:123], v[122:123], 0, v[2:3]
	v_add_co_u32_e32 v122, vcc, 0xfffd9000, v122
	s_waitcnt lgkmcnt(0)
	v_cvt_pk_bf16_f32 v41, v41, s0
	v_addc_co_u32_e32 v123, vcc, -1, v123, vcc
	global_store_short v[122:123], v41, off offset:-2560
.LBB0_1052:
	s_cmp_ge_u32 s30, s28
	s_cbranch_scc1 .LBB0_1049
	v_mov_b64_e32 v[4:5], s[46:47]
	v_mad_i64_i32 v[122:123], s[56:57], v50, s50, v[4:5]
	s_lshl_b32 s14, s29, 1
	v_mov_b32_e32 v39, v3
	v_lshl_add_u64 v[4:5], v[122:123], 0, s[14:15]
	v_lshl_add_u64 v[4:5], v[4:5], 0, v[38:39]
	v_add_co_u32_e32 v6, vcc, 0x2b000, v4
	v_mov_b32_e32 v41, v3
	s_nop 0
	v_addc_co_u32_e32 v7, vcc, 0, v5, vcc
	v_add_co_u32_e32 v8, vcc, 0x2c000, v4
	v_lshl_add_u64 v[122:123], v[122:123], 0, v[40:41]
	s_nop 0
	v_addc_co_u32_e32 v9, vcc, 0, v5, vcc
	v_add_co_u32_e32 v122, vcc, 0x2a000, v122
	global_load_dwordx4 v[4:7], v[6:7], off offset:3584
	s_nop 0
	global_load_dwordx4 v[8:11], v[8:9], off offset:512
	v_addc_co_u32_e32 v123, vcc, 0, v123, vcc
	global_load_ushort v39, v[122:123], off
	s_branch .LBB0_1049

.LBB0_1093:
	v_lshl_add_u32 v13, s24, 2, v36
	v_add_u32_e32 v2, v13, v34
	s_waitcnt lgkmcnt(9)
	v_mul_f32_e32 v29, v7, v55
	v_fmac_f32_e32 v29, v6, v54
	v_fmac_f32_e32 v29, v5, v53
	v_fmac_f32_e32 v29, v4, v52
	s_waitcnt lgkmcnt(3)
	v_mul_f32_e32 v94, v76, v92
	v_mul_f32_e32 v95, v77, v92
	v_add_f32_dpp v29, v29, v29 quad_perm:[1,0,3,2] row_mask:0xf bank_mask:0xf bound_ctrl:1
	v_mul_f32_e32 v96, v78, v92
	v_mul_f32_e32 v92, v79, v92
	v_add_f32_dpp v29, v29, v29 quad_perm:[2,3,0,1] row_mask:0xf bank_mask:0xf bound_ctrl:1
	s_nop 1
	v_add_f32_dpp v29, v29, v29 row_half_mirror row_mask:0xf bank_mask:0xf bound_ctrl:1
	s_nop 1
	v_add_f32_dpp v29, v29, v29 row_mirror row_mask:0xf bank_mask:0xf bound_ctrl:1
	v_fmac_f32_e32 v92, v29, v71
	v_fmac_f32_e32 v96, v29, v70
	v_fmac_f32_e32 v92, v7, v63
	v_fmac_f32_e32 v94, v29, v68
	v_fmac_f32_e32 v95, v29, v69
	v_fmac_f32_e32 v96, v6, v62
	v_fmac_f32_e32 v95, v5, v61
	s_waitcnt lgkmcnt(1)
	v_mul_f32_e32 v29, v87, v92
	v_fmac_f32_e32 v94, v4, v60
	v_fmac_f32_e32 v29, v96, v86
	s_nop 0
	v_fmac_f32_e32 v29, v95, v85
	v_fmac_f32_e32 v29, v94, v84
	ds_read_b128 v[4:7], v30 offset:12800
	ds_read_b128 v[52:55], v30 offset:8704
	ds_read_b128 v[60:63], v30 offset:4608
	ds_read_b128 v[68:71], v30 offset:512
	ds_read_b128 v[76:79], v30 offset:16896
	ds_read_b32 v97, v33 offset:20608
	v_mul_f32_e32 v59, v59, v92
	v_fmac_f32_e32 v59, v96, v58
	v_fmac_f32_e32 v59, v95, v57
	v_fmac_f32_e32 v59, v94, v56
	v_add_f32_dpp v29, v29, v29 quad_perm:[1,0,3,2] row_mask:0xf bank_mask:0xf bound_ctrl:1
	v_mul_f32_e32 v98, v80, v93
	v_add_f32_dpp v56, v59, v59 quad_perm:[1,0,3,2] row_mask:0xf bank_mask:0xf bound_ctrl:1
	v_add_f32_dpp v29, v29, v29 quad_perm:[2,3,0,1] row_mask:0xf bank_mask:0xf bound_ctrl:1
	s_nop 0
	v_add_f32_dpp v56, v56, v56 quad_perm:[2,3,0,1] row_mask:0xf bank_mask:0xf bound_ctrl:1
	v_add_f32_dpp v29, v29, v29 row_half_mirror row_mask:0xf bank_mask:0xf bound_ctrl:1
	s_nop 0
	v_add_f32_dpp v56, v56, v56 row_half_mirror row_mask:0xf bank_mask:0xf bound_ctrl:1
	v_add_f32_dpp v29, v29, v29 row_mirror row_mask:0xf bank_mask:0xf bound_ctrl:1
	ds_write_b32 v13, v29 offset:21504
	s_nop 0
	v_add_f32_dpp v29, v56, v56 row_mirror row_mask:0xf bank_mask:0xf bound_ctrl:1
	v_fmac_f32_e32 v98, v29, v72
	v_fmac_f32_e32 v98, v94, v64
	v_mul_f32_e32 v94, v81, v93
	v_fmac_f32_e32 v94, v29, v73
	v_fmac_f32_e32 v94, v95, v65
	v_mul_f32_e32 v95, v82, v93
	v_mul_f32_e32 v93, v83, v93
	v_fmac_f32_e32 v93, v29, v75
	v_fmac_f32_e32 v95, v29, v74
	v_fmac_f32_e32 v93, v92, v67
	v_fmac_f32_e32 v95, v96, v66
	s_waitcnt lgkmcnt(7)
	v_mul_f32_e32 v29, v91, v93
	v_fmac_f32_e32 v29, v95, v90
	v_fmac_f32_e32 v29, v94, v89
	v_fmac_f32_e32 v29, v98, v88
	ds_read_b128 v[56:59], v30 offset:13056
	ds_read_b128 v[64:67], v30 offset:8960
	ds_read_b128 v[72:75], v30 offset:4864
	ds_read_b128 v[80:83], v30 offset:768
	ds_read_b128 v[84:87], v30 offset:17152
	ds_read_b32 v88, v33 offset:20672
	s_waitcnt lgkmcnt(12)
	v_mul_f32_e32 v7, v7, v93
	v_fmac_f32_e32 v7, v95, v6
	v_fmac_f32_e32 v7, v94, v5
	v_fmac_f32_e32 v7, v98, v4
	s_waitcnt lgkmcnt(7)
	v_mul_f32_e32 v91, v55, v97
	v_mul_f32_e32 v90, v54, v97
	v_add_f32_dpp v4, v7, v7 quad_perm:[1,0,3,2] row_mask:0xf bank_mask:0xf bound_ctrl:1
	v_add_f32_dpp v5, v29, v29 quad_perm:[1,0,3,2] row_mask:0xf bank_mask:0xf bound_ctrl:1
	v_mul_f32_e32 v89, v53, v97
	v_add_f32_dpp v4, v4, v4 quad_perm:[2,3,0,1] row_mask:0xf bank_mask:0xf bound_ctrl:1
	v_add_f32_dpp v5, v5, v5 quad_perm:[2,3,0,1] row_mask:0xf bank_mask:0xf bound_ctrl:1
	v_mul_f32_e32 v29, v52, v97
	v_add_f32_dpp v4, v4, v4 row_half_mirror row_mask:0xf bank_mask:0xf bound_ctrl:1
	v_add_f32_dpp v5, v5, v5 row_half_mirror row_mask:0xf bank_mask:0xf bound_ctrl:1
	v_add_u32_e32 v6, v2, v51
	v_add_f32_dpp v4, v4, v4 row_mirror row_mask:0xf bank_mask:0xf bound_ctrl:1
	v_fmac_f32_e32 v91, v4, v79
	v_fmac_f32_e32 v90, v4, v78
	v_fmac_f32_e32 v91, v93, v63
	v_fmac_f32_e32 v89, v4, v77
	v_fmac_f32_e32 v90, v95, v62
	v_fmac_f32_e32 v29, v4, v76
	v_mul_f32_e32 v92, v71, v91
	v_fmac_f32_e32 v89, v94, v61
	v_add_f32_dpp v5, v5, v5 row_mirror row_mask:0xf bank_mask:0xf bound_ctrl:1
	v_fmac_f32_e32 v92, v90, v70
	v_fmac_f32_e32 v29, v98, v60
	ds_write_b32 v6, v5 offset:21504
	v_fmac_f32_e32 v92, v89, v69
	s_nop 0
	v_fmac_f32_e32 v92, v29, v68
	ds_read_b128 v[4:7], v30 offset:13312
	ds_read_b128 v[52:55], v30 offset:9216
	ds_read_b128 v[60:63], v30 offset:5120
	ds_read_b128 v[68:71], v30 offset:1024
	ds_read_b128 v[76:79], v30 offset:17408
	ds_read_b32 v93, v33 offset:20736
	s_waitcnt lgkmcnt(12)
	v_mul_f32_e32 v59, v59, v91
	v_fmac_f32_e32 v59, v90, v58
	v_fmac_f32_e32 v59, v89, v57
	v_fmac_f32_e32 v59, v29, v56
	v_add_f32_dpp v57, v92, v92 quad_perm:[1,0,3,2] row_mask:0xf bank_mask:0xf bound_ctrl:1
	s_waitcnt lgkmcnt(7)
	v_mul_f32_e32 v92, v64, v88
	v_add_f32_dpp v56, v59, v59 quad_perm:[1,0,3,2] row_mask:0xf bank_mask:0xf bound_ctrl:1
	v_add_f32_dpp v57, v57, v57 quad_perm:[2,3,0,1] row_mask:0xf bank_mask:0xf bound_ctrl:1
	v_add_u32_e32 v58, v13, v37
	v_add_f32_dpp v56, v56, v56 quad_perm:[2,3,0,1] row_mask:0xf bank_mask:0xf bound_ctrl:1
	v_add_f32_dpp v57, v57, v57 row_half_mirror row_mask:0xf bank_mask:0xf bound_ctrl:1
	s_nop 0
	v_add_f32_dpp v56, v56, v56 row_half_mirror row_mask:0xf bank_mask:0xf bound_ctrl:1
	v_add_f32_dpp v57, v57, v57 row_mirror row_mask:0xf bank_mask:0xf bound_ctrl:1
	ds_write_b32 v58, v57 offset:21504
	v_add_f32_dpp v56, v56, v56 row_mirror row_mask:0xf bank_mask:0xf bound_ctrl:1
	v_fmac_f32_e32 v92, v56, v84
	v_fmac_f32_e32 v92, v29, v72
	v_mul_f32_e32 v29, v65, v88
	v_fmac_f32_e32 v29, v56, v85
	v_fmac_f32_e32 v29, v89, v73
	v_mul_f32_e32 v89, v66, v88
	v_mul_f32_e32 v88, v67, v88
	v_fmac_f32_e32 v88, v56, v87
	v_fmac_f32_e32 v89, v56, v86
	v_fmac_f32_e32 v88, v91, v75
	v_fmac_f32_e32 v89, v90, v74
	s_nop 0
	v_mul_f32_e32 v90, v83, v88
	v_fmac_f32_e32 v90, v89, v82
	v_fmac_f32_e32 v90, v29, v81
	v_fmac_f32_e32 v90, v92, v80
	ds_read_b128 v[56:59], v30 offset:13568
	ds_read_b128 v[64:67], v30 offset:9472
	ds_read_b128 v[72:75], v30 offset:5376
	ds_read_b128 v[80:83], v30 offset:1280
	ds_read_b128 v[84:87], v30 offset:17664
	ds_read_b32 v91, v33 offset:20800
	s_waitcnt lgkmcnt(12)
	v_mul_f32_e32 v7, v7, v88
	v_fmac_f32_e32 v7, v89, v6
	v_fmac_f32_e32 v7, v29, v5
	v_fmac_f32_e32 v7, v92, v4
	v_add_f32_dpp v5, v90, v90 quad_perm:[1,0,3,2] row_mask:0xf bank_mask:0xf bound_ctrl:1
	s_waitcnt lgkmcnt(7)
	v_mul_f32_e32 v90, v52, v93
	v_add_f32_dpp v4, v7, v7 quad_perm:[1,0,3,2] row_mask:0xf bank_mask:0xf bound_ctrl:1
	v_add_f32_dpp v5, v5, v5 quad_perm:[2,3,0,1] row_mask:0xf bank_mask:0xf bound_ctrl:1
	v_add_u32_e32 v6, v13, v38
	v_add_f32_dpp v4, v4, v4 quad_perm:[2,3,0,1] row_mask:0xf bank_mask:0xf bound_ctrl:1
	v_add_f32_dpp v5, v5, v5 row_half_mirror row_mask:0xf bank_mask:0xf bound_ctrl:1
	s_nop 0
	v_add_f32_dpp v4, v4, v4 row_half_mirror row_mask:0xf bank_mask:0xf bound_ctrl:1
	v_add_f32_dpp v5, v5, v5 row_mirror row_mask:0xf bank_mask:0xf bound_ctrl:1
	ds_write_b32 v6, v5 offset:21504
	v_add_f32_dpp v4, v4, v4 row_mirror row_mask:0xf bank_mask:0xf bound_ctrl:1
	v_fmac_f32_e32 v90, v4, v76
	v_fmac_f32_e32 v90, v92, v60
	v_mul_f32_e32 v92, v53, v93
	v_fmac_f32_e32 v92, v4, v77
	v_fmac_f32_e32 v92, v29, v61
	v_mul_f32_e32 v29, v54, v93
	v_fmac_f32_e32 v29, v4, v78
	v_fmac_f32_e32 v29, v89, v62
	v_mul_f32_e32 v89, v55, v93
	v_fmac_f32_e32 v89, v4, v79
	v_fmac_f32_e32 v89, v88, v63
	s_nop 0
	v_mul_f32_e32 v88, v71, v89
	v_fmac_f32_e32 v88, v29, v70
	v_fmac_f32_e32 v88, v92, v69
	v_fmac_f32_e32 v88, v90, v68
	ds_read_b128 v[4:7], v30 offset:13824
	ds_read_b128 v[52:55], v30 offset:9728
	ds_read_b128 v[60:63], v30 offset:5632
	ds_read_b128 v[68:71], v30 offset:1536
	ds_read_b128 v[76:79], v30 offset:17920
	ds_read_b32 v93, v33 offset:20864
	s_waitcnt lgkmcnt(12)
	v_mul_f32_e32 v59, v59, v89
	v_fmac_f32_e32 v59, v29, v58
	v_fmac_f32_e32 v59, v92, v57
	v_fmac_f32_e32 v59, v90, v56
	v_add_f32_dpp v57, v88, v88 quad_perm:[1,0,3,2] row_mask:0xf bank_mask:0xf bound_ctrl:1
	s_waitcnt lgkmcnt(7)
	v_mul_f32_e32 v88, v64, v91
	v_add_f32_dpp v56, v59, v59 quad_perm:[1,0,3,2] row_mask:0xf bank_mask:0xf bound_ctrl:1
	v_add_f32_dpp v57, v57, v57 quad_perm:[2,3,0,1] row_mask:0xf bank_mask:0xf bound_ctrl:1
	v_add_u32_e32 v58, v13, v39
	v_add_f32_dpp v56, v56, v56 quad_perm:[2,3,0,1] row_mask:0xf bank_mask:0xf bound_ctrl:1
	v_add_f32_dpp v57, v57, v57 row_half_mirror row_mask:0xf bank_mask:0xf bound_ctrl:1
	s_nop 0
	v_add_f32_dpp v56, v56, v56 row_half_mirror row_mask:0xf bank_mask:0xf bound_ctrl:1
	v_add_f32_dpp v57, v57, v57 row_mirror row_mask:0xf bank_mask:0xf bound_ctrl:1
	ds_write_b32 v58, v57 offset:21504
	v_add_f32_dpp v56, v56, v56 row_mirror row_mask:0xf bank_mask:0xf bound_ctrl:1
	v_fmac_f32_e32 v88, v56, v84
	v_fmac_f32_e32 v88, v90, v72
	v_mul_f32_e32 v90, v65, v91
	v_fmac_f32_e32 v90, v56, v85
	v_fmac_f32_e32 v90, v92, v73
	v_mul_f32_e32 v92, v66, v91
	v_fmac_f32_e32 v92, v56, v86
	v_fmac_f32_e32 v92, v29, v74
	v_mul_f32_e32 v29, v67, v91
	v_fmac_f32_e32 v29, v56, v87
	v_fmac_f32_e32 v29, v89, v75
	s_nop 0
	v_mul_f32_e32 v89, v83, v29
	v_fmac_f32_e32 v89, v92, v82
	v_fmac_f32_e32 v89, v90, v81
	v_fmac_f32_e32 v89, v88, v80
	ds_read_b128 v[56:59], v30 offset:14080
	ds_read_b128 v[64:67], v30 offset:9984
	ds_read_b128 v[72:75], v30 offset:5888
	ds_read_b128 v[80:83], v30 offset:1792
	ds_read_b128 v[84:87], v30 offset:18176
	ds_read_b32 v91, v33 offset:20928
	s_waitcnt lgkmcnt(12)
	v_mul_f32_e32 v7, v7, v29
	v_fmac_f32_e32 v7, v92, v6
	v_fmac_f32_e32 v7, v90, v5
	v_fmac_f32_e32 v7, v88, v4
	v_add_f32_dpp v5, v89, v89 quad_perm:[1,0,3,2] row_mask:0xf bank_mask:0xf bound_ctrl:1
	s_waitcnt lgkmcnt(7)
	v_mul_f32_e32 v89, v52, v93
	v_add_f32_dpp v4, v7, v7 quad_perm:[1,0,3,2] row_mask:0xf bank_mask:0xf bound_ctrl:1
	v_add_f32_dpp v5, v5, v5 quad_perm:[2,3,0,1] row_mask:0xf bank_mask:0xf bound_ctrl:1
	v_add_u32_e32 v6, v13, v40
	v_add_f32_dpp v4, v4, v4 quad_perm:[2,3,0,1] row_mask:0xf bank_mask:0xf bound_ctrl:1
	v_add_f32_dpp v5, v5, v5 row_half_mirror row_mask:0xf bank_mask:0xf bound_ctrl:1
	s_nop 0
	v_add_f32_dpp v4, v4, v4 row_half_mirror row_mask:0xf bank_mask:0xf bound_ctrl:1
	v_add_f32_dpp v5, v5, v5 row_mirror row_mask:0xf bank_mask:0xf bound_ctrl:1
	ds_write_b32 v6, v5 offset:21504
	v_add_f32_dpp v4, v4, v4 row_mirror row_mask:0xf bank_mask:0xf bound_ctrl:1
	v_fmac_f32_e32 v89, v4, v76
	v_fmac_f32_e32 v89, v88, v60
	v_mul_f32_e32 v88, v53, v93
	v_fmac_f32_e32 v88, v4, v77
	v_fmac_f32_e32 v88, v90, v61
	v_mul_f32_e32 v90, v54, v93
	v_fmac_f32_e32 v90, v4, v78
	v_fmac_f32_e32 v90, v92, v62
	v_mul_f32_e32 v92, v55, v93
	v_fmac_f32_e32 v92, v4, v79
	v_fmac_f32_e32 v92, v29, v63
	s_nop 0
	v_mul_f32_e32 v29, v71, v92
	v_fmac_f32_e32 v29, v90, v70
	v_fmac_f32_e32 v29, v88, v69
	v_fmac_f32_e32 v29, v89, v68
	ds_read_b128 v[4:7], v30 offset:14336
	ds_read_b128 v[52:55], v30 offset:10240
	ds_read_b128 v[60:63], v30 offset:6144
	ds_read_b128 v[68:71], v30 offset:2048
	ds_read_b128 v[76:79], v30 offset:18432
	ds_read_b32 v93, v33 offset:20992
	s_waitcnt lgkmcnt(12)
	v_mul_f32_e32 v59, v59, v92
	v_fmac_f32_e32 v59, v90, v58
	v_fmac_f32_e32 v59, v88, v57
	v_fmac_f32_e32 v59, v89, v56
	v_add_f32_dpp v29, v29, v29 quad_perm:[1,0,3,2] row_mask:0xf bank_mask:0xf bound_ctrl:1
	v_add_u32_e32 v57, v13, v41
	v_add_f32_dpp v56, v59, v59 quad_perm:[1,0,3,2] row_mask:0xf bank_mask:0xf bound_ctrl:1
	v_add_f32_dpp v29, v29, v29 quad_perm:[2,3,0,1] row_mask:0xf bank_mask:0xf bound_ctrl:1
	s_waitcnt lgkmcnt(7)
	v_mul_f32_e32 v94, v64, v91
	v_add_f32_dpp v56, v56, v56 quad_perm:[2,3,0,1] row_mask:0xf bank_mask:0xf bound_ctrl:1
	v_add_f32_dpp v29, v29, v29 row_half_mirror row_mask:0xf bank_mask:0xf bound_ctrl:1
	s_nop 0
	v_add_f32_dpp v56, v56, v56 row_half_mirror row_mask:0xf bank_mask:0xf bound_ctrl:1
	v_add_f32_dpp v29, v29, v29 row_mirror row_mask:0xf bank_mask:0xf bound_ctrl:1
	ds_write_b32 v57, v29 offset:21504
	s_nop 0
	v_add_f32_dpp v29, v56, v56 row_mirror row_mask:0xf bank_mask:0xf bound_ctrl:1
	v_fmac_f32_e32 v94, v29, v84
	v_fmac_f32_e32 v94, v89, v72
	v_mul_f32_e32 v89, v65, v91
	v_fmac_f32_e32 v89, v29, v85
	v_fmac_f32_e32 v89, v88, v73
	v_mul_f32_e32 v88, v66, v91
	v_fmac_f32_e32 v88, v29, v86
	v_fmac_f32_e32 v88, v90, v74
	v_mul_f32_e32 v90, v67, v91
	v_fmac_f32_e32 v90, v29, v87
	v_fmac_f32_e32 v90, v92, v75
	s_nop 0
	v_mul_f32_e32 v29, v83, v90
	v_fmac_f32_e32 v29, v88, v82
	v_fmac_f32_e32 v29, v89, v81
	v_fmac_f32_e32 v29, v94, v80
	ds_read_b128 v[56:59], v30 offset:14592
	ds_read_b128 v[64:67], v30 offset:10496
	ds_read_b128 v[72:75], v30 offset:6400
	ds_read_b128 v[80:83], v30 offset:2304
	ds_read_b128 v[84:87], v30 offset:18688
	ds_read_b32 v91, v33 offset:21056
	s_waitcnt lgkmcnt(12)
	v_mul_f32_e32 v7, v7, v90
	v_fmac_f32_e32 v7, v88, v6
	v_fmac_f32_e32 v7, v89, v5
	v_fmac_f32_e32 v7, v94, v4
	s_waitcnt lgkmcnt(7)
	v_mul_f32_e32 v92, v53, v93
	v_add_f32_dpp v5, v29, v29 quad_perm:[1,0,3,2] row_mask:0xf bank_mask:0xf bound_ctrl:1
	v_add_f32_dpp v4, v7, v7 quad_perm:[1,0,3,2] row_mask:0xf bank_mask:0xf bound_ctrl:1
	v_mul_f32_e32 v29, v52, v93
	v_add_f32_dpp v5, v5, v5 quad_perm:[2,3,0,1] row_mask:0xf bank_mask:0xf bound_ctrl:1
	v_add_f32_dpp v4, v4, v4 quad_perm:[2,3,0,1] row_mask:0xf bank_mask:0xf bound_ctrl:1
	v_add_u32_e32 v6, v13, v43
	v_add_f32_dpp v5, v5, v5 row_half_mirror row_mask:0xf bank_mask:0xf bound_ctrl:1
	v_add_f32_dpp v4, v4, v4 row_half_mirror row_mask:0xf bank_mask:0xf bound_ctrl:1
	s_nop 0
	v_add_f32_dpp v5, v5, v5 row_mirror row_mask:0xf bank_mask:0xf bound_ctrl:1
	v_add_f32_dpp v4, v4, v4 row_mirror row_mask:0xf bank_mask:0xf bound_ctrl:1
	v_fmac_f32_e32 v92, v4, v77
	v_fmac_f32_e32 v92, v89, v61
	v_mul_f32_e32 v89, v54, v93
	v_fmac_f32_e32 v89, v4, v78
	v_fmac_f32_e32 v89, v88, v62
	v_mul_f32_e32 v88, v55, v93
	v_fmac_f32_e32 v88, v4, v79
	v_fmac_f32_e32 v88, v90, v63
	v_fmac_f32_e32 v29, v4, v76
	v_mul_f32_e32 v90, v71, v88
	v_fmac_f32_e32 v29, v94, v60
	v_fmac_f32_e32 v90, v89, v70
	ds_write_b32 v6, v5 offset:21504
	v_fmac_f32_e32 v90, v92, v69
	s_nop 0
	v_fmac_f32_e32 v90, v29, v68
	ds_read_b128 v[4:7], v30 offset:14848
	ds_read_b128 v[52:55], v30 offset:10752
	ds_read_b128 v[60:63], v30 offset:6656
	ds_read_b128 v[68:71], v30 offset:2560
	ds_read_b128 v[76:79], v30 offset:18944
	ds_read_b32 v93, v33 offset:21120
	s_waitcnt lgkmcnt(12)
	v_mul_f32_e32 v59, v59, v88
	v_fmac_f32_e32 v59, v89, v58
	v_fmac_f32_e32 v59, v92, v57
	v_fmac_f32_e32 v59, v29, v56
	v_add_f32_dpp v57, v90, v90 quad_perm:[1,0,3,2] row_mask:0xf bank_mask:0xf bound_ctrl:1
	s_waitcnt lgkmcnt(7)
	v_mul_f32_e32 v90, v64, v91
	v_add_f32_dpp v56, v59, v59 quad_perm:[1,0,3,2] row_mask:0xf bank_mask:0xf bound_ctrl:1
	v_add_f32_dpp v57, v57, v57 quad_perm:[2,3,0,1] row_mask:0xf bank_mask:0xf bound_ctrl:1
	v_add_u32_e32 v58, v13, v44
	v_add_f32_dpp v56, v56, v56 quad_perm:[2,3,0,1] row_mask:0xf bank_mask:0xf bound_ctrl:1
	v_add_f32_dpp v57, v57, v57 row_half_mirror row_mask:0xf bank_mask:0xf bound_ctrl:1
	s_nop 0
	v_add_f32_dpp v56, v56, v56 row_half_mirror row_mask:0xf bank_mask:0xf bound_ctrl:1
	v_add_f32_dpp v57, v57, v57 row_mirror row_mask:0xf bank_mask:0xf bound_ctrl:1
	ds_write_b32 v58, v57 offset:21504
	v_add_f32_dpp v56, v56, v56 row_mirror row_mask:0xf bank_mask:0xf bound_ctrl:1
	v_fmac_f32_e32 v90, v56, v84
	v_fmac_f32_e32 v90, v29, v72
	v_mul_f32_e32 v29, v65, v91
	v_fmac_f32_e32 v29, v56, v85
	v_fmac_f32_e32 v29, v92, v73
	v_mul_f32_e32 v92, v66, v91
	v_fmac_f32_e32 v92, v56, v86
	v_fmac_f32_e32 v92, v89, v74
	v_mul_f32_e32 v89, v67, v91
	v_fmac_f32_e32 v89, v56, v87
	v_fmac_f32_e32 v89, v88, v75
	s_nop 0
	v_mul_f32_e32 v88, v83, v89
	v_fmac_f32_e32 v88, v92, v82
	v_fmac_f32_e32 v88, v29, v81
	v_fmac_f32_e32 v88, v90, v80
	ds_read_b128 v[56:59], v30 offset:15104
	ds_read_b128 v[64:67], v30 offset:11008
	ds_read_b128 v[72:75], v30 offset:6912
	ds_read_b128 v[80:83], v30 offset:2816
	ds_read_b128 v[84:87], v30 offset:19200
	ds_read_b32 v91, v33 offset:21184
	s_waitcnt lgkmcnt(12)
	v_mul_f32_e32 v7, v7, v89
	v_fmac_f32_e32 v7, v92, v6
	v_fmac_f32_e32 v7, v29, v5
	v_fmac_f32_e32 v7, v90, v4
	v_add_f32_dpp v5, v88, v88 quad_perm:[1,0,3,2] row_mask:0xf bank_mask:0xf bound_ctrl:1
	s_waitcnt lgkmcnt(7)
	v_mul_f32_e32 v88, v52, v93
	v_add_f32_dpp v4, v7, v7 quad_perm:[1,0,3,2] row_mask:0xf bank_mask:0xf bound_ctrl:1
	v_add_f32_dpp v5, v5, v5 quad_perm:[2,3,0,1] row_mask:0xf bank_mask:0xf bound_ctrl:1
	v_add_u32_e32 v6, v13, v45
	v_add_f32_dpp v4, v4, v4 quad_perm:[2,3,0,1] row_mask:0xf bank_mask:0xf bound_ctrl:1
	v_add_f32_dpp v5, v5, v5 row_half_mirror row_mask:0xf bank_mask:0xf bound_ctrl:1
	s_nop 0
	v_add_f32_dpp v4, v4, v4 row_half_mirror row_mask:0xf bank_mask:0xf bound_ctrl:1
	v_add_f32_dpp v5, v5, v5 row_mirror row_mask:0xf bank_mask:0xf bound_ctrl:1
	ds_write_b32 v6, v5 offset:21504
	v_add_f32_dpp v4, v4, v4 row_mirror row_mask:0xf bank_mask:0xf bound_ctrl:1
	v_fmac_f32_e32 v88, v4, v76
	v_fmac_f32_e32 v88, v90, v60
	v_mul_f32_e32 v90, v53, v93
	v_fmac_f32_e32 v90, v4, v77
	v_fmac_f32_e32 v90, v29, v61
	v_mul_f32_e32 v29, v54, v93
	v_fmac_f32_e32 v29, v4, v78
	v_fmac_f32_e32 v29, v92, v62
	v_mul_f32_e32 v92, v55, v93
	v_fmac_f32_e32 v92, v4, v79
	v_fmac_f32_e32 v92, v89, v63
	s_nop 0
	v_mul_f32_e32 v89, v71, v92
	v_fmac_f32_e32 v89, v29, v70
	v_fmac_f32_e32 v89, v90, v69
	v_fmac_f32_e32 v89, v88, v68
	ds_read_b128 v[4:7], v30 offset:15360
	ds_read_b128 v[52:55], v30 offset:11264
	ds_read_b128 v[60:63], v30 offset:7168
	ds_read_b128 v[68:71], v30 offset:3072
	ds_read_b128 v[76:79], v30 offset:19456
	ds_read_b32 v93, v33 offset:21248
	s_waitcnt lgkmcnt(12)
	v_mul_f32_e32 v59, v59, v92
	v_fmac_f32_e32 v59, v29, v58
	v_fmac_f32_e32 v59, v90, v57
	v_fmac_f32_e32 v59, v88, v56
	v_add_f32_dpp v57, v89, v89 quad_perm:[1,0,3,2] row_mask:0xf bank_mask:0xf bound_ctrl:1
	s_waitcnt lgkmcnt(7)
	v_mul_f32_e32 v89, v64, v91
	v_add_f32_dpp v56, v59, v59 quad_perm:[1,0,3,2] row_mask:0xf bank_mask:0xf bound_ctrl:1
	v_add_f32_dpp v57, v57, v57 quad_perm:[2,3,0,1] row_mask:0xf bank_mask:0xf bound_ctrl:1
	v_add_u32_e32 v58, v13, v46
	v_add_f32_dpp v56, v56, v56 quad_perm:[2,3,0,1] row_mask:0xf bank_mask:0xf bound_ctrl:1
	v_add_f32_dpp v57, v57, v57 row_half_mirror row_mask:0xf bank_mask:0xf bound_ctrl:1
	s_nop 0
	v_add_f32_dpp v56, v56, v56 row_half_mirror row_mask:0xf bank_mask:0xf bound_ctrl:1
	v_add_f32_dpp v57, v57, v57 row_mirror row_mask:0xf bank_mask:0xf bound_ctrl:1
	ds_write_b32 v58, v57 offset:21504
	v_add_f32_dpp v56, v56, v56 row_mirror row_mask:0xf bank_mask:0xf bound_ctrl:1
	v_fmac_f32_e32 v89, v56, v84
	v_fmac_f32_e32 v89, v88, v72
	v_mul_f32_e32 v88, v65, v91
	v_fmac_f32_e32 v88, v56, v85
	v_fmac_f32_e32 v88, v90, v73
	v_mul_f32_e32 v90, v66, v91
	v_fmac_f32_e32 v90, v56, v86
	v_fmac_f32_e32 v90, v29, v74
	v_mul_f32_e32 v29, v67, v91
	v_fmac_f32_e32 v29, v56, v87
	v_fmac_f32_e32 v29, v92, v75
	s_nop 0
	v_mul_f32_e32 v91, v83, v29
	v_fmac_f32_e32 v91, v90, v82
	v_fmac_f32_e32 v91, v88, v81
	v_fmac_f32_e32 v91, v89, v80
	ds_read_b128 v[56:59], v30 offset:15616
	ds_read_b128 v[64:67], v30 offset:11520
	ds_read_b128 v[72:75], v30 offset:7424
	ds_read_b128 v[80:83], v30 offset:3328
	ds_read_b128 v[84:87], v30 offset:19712
	ds_read_b32 v92, v33 offset:21312
	s_waitcnt lgkmcnt(12)
	v_mul_f32_e32 v7, v7, v29
	v_fmac_f32_e32 v7, v90, v6
	v_fmac_f32_e32 v7, v88, v5
	v_fmac_f32_e32 v7, v89, v4
	v_add_f32_dpp v5, v91, v91 quad_perm:[1,0,3,2] row_mask:0xf bank_mask:0xf bound_ctrl:1
	s_waitcnt lgkmcnt(7)
	v_mul_f32_e32 v91, v52, v93
	v_add_f32_dpp v4, v7, v7 quad_perm:[1,0,3,2] row_mask:0xf bank_mask:0xf bound_ctrl:1
	v_add_f32_dpp v5, v5, v5 quad_perm:[2,3,0,1] row_mask:0xf bank_mask:0xf bound_ctrl:1
	v_add_u32_e32 v6, v13, v47
	v_add_f32_dpp v4, v4, v4 quad_perm:[2,3,0,1] row_mask:0xf bank_mask:0xf bound_ctrl:1
	v_add_f32_dpp v5, v5, v5 row_half_mirror row_mask:0xf bank_mask:0xf bound_ctrl:1
	s_nop 0
	v_add_f32_dpp v4, v4, v4 row_half_mirror row_mask:0xf bank_mask:0xf bound_ctrl:1
	v_add_f32_dpp v5, v5, v5 row_mirror row_mask:0xf bank_mask:0xf bound_ctrl:1
	ds_write_b32 v6, v5 offset:21504
	v_add_f32_dpp v4, v4, v4 row_mirror row_mask:0xf bank_mask:0xf bound_ctrl:1
	v_fmac_f32_e32 v91, v4, v76
	v_fmac_f32_e32 v91, v89, v60
	v_mul_f32_e32 v89, v53, v93
	v_fmac_f32_e32 v89, v4, v77
	v_fmac_f32_e32 v89, v88, v61
	v_mul_f32_e32 v88, v54, v93
	v_fmac_f32_e32 v88, v4, v78
	v_fmac_f32_e32 v88, v90, v62
	v_mul_f32_e32 v90, v55, v93
	v_fmac_f32_e32 v90, v4, v79
	v_fmac_f32_e32 v90, v29, v63
	s_nop 0
	v_mul_f32_e32 v29, v71, v90
	v_fmac_f32_e32 v29, v88, v70
	v_fmac_f32_e32 v29, v89, v69
	v_fmac_f32_e32 v29, v91, v68
	ds_read_b128 v[4:7], v30 offset:15872
	ds_read_b128 v[52:55], v30 offset:11776
	ds_read_b128 v[60:63], v30 offset:7680
	ds_read_b128 v[68:71], v30 offset:3584
	ds_read_b128 v[76:79], v30 offset:19968
	ds_read_b32 v93, v33 offset:21376
	s_waitcnt lgkmcnt(12)
	v_mul_f32_e32 v59, v59, v90
	v_fmac_f32_e32 v59, v88, v58
	v_fmac_f32_e32 v59, v89, v57
	v_fmac_f32_e32 v59, v91, v56
	v_add_f32_dpp v29, v29, v29 quad_perm:[1,0,3,2] row_mask:0xf bank_mask:0xf bound_ctrl:1
	v_add_u32_e32 v57, v13, v48
	v_add_f32_dpp v56, v59, v59 quad_perm:[1,0,3,2] row_mask:0xf bank_mask:0xf bound_ctrl:1
	v_add_f32_dpp v29, v29, v29 quad_perm:[2,3,0,1] row_mask:0xf bank_mask:0xf bound_ctrl:1
	s_waitcnt lgkmcnt(7)
	v_mul_f32_e32 v94, v64, v92
	v_add_f32_dpp v56, v56, v56 quad_perm:[2,3,0,1] row_mask:0xf bank_mask:0xf bound_ctrl:1
	v_add_f32_dpp v29, v29, v29 row_half_mirror row_mask:0xf bank_mask:0xf bound_ctrl:1
	s_nop 0
	v_add_f32_dpp v56, v56, v56 row_half_mirror row_mask:0xf bank_mask:0xf bound_ctrl:1
	v_add_f32_dpp v29, v29, v29 row_mirror row_mask:0xf bank_mask:0xf bound_ctrl:1
	ds_write_b32 v57, v29 offset:21504
	s_nop 0
	v_add_f32_dpp v29, v56, v56 row_mirror row_mask:0xf bank_mask:0xf bound_ctrl:1
	v_fmac_f32_e32 v94, v29, v84
	v_fmac_f32_e32 v94, v91, v72
	v_mul_f32_e32 v91, v65, v92
	v_fmac_f32_e32 v91, v29, v85
	v_fmac_f32_e32 v91, v89, v73
	v_mul_f32_e32 v89, v66, v92
	v_fmac_f32_e32 v89, v29, v86
	v_fmac_f32_e32 v89, v88, v74
	v_mul_f32_e32 v88, v67, v92
	v_fmac_f32_e32 v88, v29, v87
	v_fmac_f32_e32 v88, v90, v75
	s_nop 0
	v_mul_f32_e32 v29, v83, v88
	v_fmac_f32_e32 v29, v89, v82
	v_fmac_f32_e32 v29, v91, v81
	v_fmac_f32_e32 v29, v94, v80
	ds_read_b128 v[56:59], v30 offset:16128
	ds_read_b128 v[64:67], v30 offset:12032
	ds_read_b128 v[72:75], v30 offset:7936
	ds_read_b128 v[80:83], v30 offset:3840
	ds_read_b128 v[84:87], v30 offset:20224
	ds_read_b32 v90, v33 offset:21440
	s_waitcnt lgkmcnt(12)
	v_mul_f32_e32 v7, v7, v88
	v_fmac_f32_e32 v7, v89, v6
	v_fmac_f32_e32 v7, v91, v5
	v_fmac_f32_e32 v7, v94, v4
	v_add_f32_dpp v5, v29, v29 quad_perm:[1,0,3,2] row_mask:0xf bank_mask:0xf bound_ctrl:1
	s_waitcnt lgkmcnt(7)
	v_mul_f32_e32 v29, v55, v93
	v_add_f32_dpp v4, v7, v7 quad_perm:[1,0,3,2] row_mask:0xf bank_mask:0xf bound_ctrl:1
	v_add_f32_dpp v5, v5, v5 quad_perm:[2,3,0,1] row_mask:0xf bank_mask:0xf bound_ctrl:1
	v_add_u32_e32 v6, v13, v49
	v_add_f32_dpp v4, v4, v4 quad_perm:[2,3,0,1] row_mask:0xf bank_mask:0xf bound_ctrl:1
	v_add_f32_dpp v5, v5, v5 row_half_mirror row_mask:0xf bank_mask:0xf bound_ctrl:1
	v_mul_f32_e32 v7, v54, v93
	v_add_f32_dpp v4, v4, v4 row_half_mirror row_mask:0xf bank_mask:0xf bound_ctrl:1
	v_add_f32_dpp v5, v5, v5 row_mirror row_mask:0xf bank_mask:0xf bound_ctrl:1
	ds_write_b32 v6, v5 offset:21504
	v_add_f32_dpp v4, v4, v4 row_mirror row_mask:0xf bank_mask:0xf bound_ctrl:1
	v_fmac_f32_e32 v29, v4, v79
	v_mul_f32_e32 v5, v52, v93
	v_mul_f32_e32 v6, v53, v93
	v_fmac_f32_e32 v7, v4, v78
	v_fmac_f32_e32 v29, v88, v63
	v_fmac_f32_e32 v5, v4, v76
	v_fmac_f32_e32 v6, v4, v77
	v_fmac_f32_e32 v7, v89, v62
	v_fmac_f32_e32 v6, v91, v61
	v_mul_f32_e32 v4, v71, v29
	v_fmac_f32_e32 v5, v94, v60
	v_fmac_f32_e32 v4, v7, v70
	s_nop 0
	v_fmac_f32_e32 v4, v6, v69
	v_fmac_f32_e32 v4, v5, v68
	s_waitcnt lgkmcnt(6)
	v_mul_f32_e32 v52, v59, v29
	v_fmac_f32_e32 v52, v7, v58
	v_fmac_f32_e32 v52, v6, v57
	v_fmac_f32_e32 v52, v5, v56
	v_add_f32_dpp v4, v4, v4 quad_perm:[1,0,3,2] row_mask:0xf bank_mask:0xf bound_ctrl:1
	v_add_u32_e32 v13, v13, v50
	v_add_f32_dpp v52, v52, v52 quad_perm:[1,0,3,2] row_mask:0xf bank_mask:0xf bound_ctrl:1
	v_add_f32_dpp v4, v4, v4 quad_perm:[2,3,0,1] row_mask:0xf bank_mask:0xf bound_ctrl:1
	s_nop 0
	v_add_f32_dpp v52, v52, v52 quad_perm:[2,3,0,1] row_mask:0xf bank_mask:0xf bound_ctrl:1
	v_add_f32_dpp v4, v4, v4 row_half_mirror row_mask:0xf bank_mask:0xf bound_ctrl:1
	s_nop 0
	v_add_f32_dpp v52, v52, v52 row_half_mirror row_mask:0xf bank_mask:0xf bound_ctrl:1
	v_add_f32_dpp v4, v4, v4 row_mirror row_mask:0xf bank_mask:0xf bound_ctrl:1
	ds_write_b32 v13, v4 offset:21504
	v_add_f32_dpp v13, v52, v52 row_mirror row_mask:0xf bank_mask:0xf bound_ctrl:1
	s_waitcnt lgkmcnt(2)
	v_mul_f32_e32 v4, v64, v90
	v_fmac_f32_e32 v4, v13, v84
	v_fmac_f32_e32 v4, v5, v72
	v_mul_f32_e32 v5, v65, v90
	v_fmac_f32_e32 v5, v13, v85
	v_fmac_f32_e32 v5, v6, v73
	v_mul_f32_e32 v6, v66, v90
	v_fmac_f32_e32 v6, v13, v86
	v_fmac_f32_e32 v6, v7, v74
	v_mul_f32_e32 v7, v67, v90
	v_fmac_f32_e32 v7, v13, v87
	v_fmac_f32_e32 v7, v29, v75
	s_nop 0
	v_mul_f32_e32 v13, v83, v7
	v_fmac_f32_e32 v13, v6, v82
	v_fmac_f32_e32 v13, v5, v81
	v_fmac_f32_e32 v13, v4, v80
	s_nop 1
	v_add_f32_dpp v13, v13, v13 quad_perm:[1,0,3,2] row_mask:0xf bank_mask:0xf bound_ctrl:1
	s_nop 1
	v_add_f32_dpp v13, v13, v13 quad_perm:[2,3,0,1] row_mask:0xf bank_mask:0xf bound_ctrl:1
	s_nop 1
	v_add_f32_dpp v13, v13, v13 row_half_mirror row_mask:0xf bank_mask:0xf bound_ctrl:1
	s_nop 1
	v_add_f32_dpp v13, v13, v13 row_mirror row_mask:0xf bank_mask:0xf bound_ctrl:1
	ds_write_b32 v2, v13 offset:21504
	s_addk_i32 s10, 0x100
	s_add_i32 s3, s3, 1
	s_cmp_lg_u32 s11, s10
	v_add_u32_e32 v28, 16, v28
	s_waitcnt lgkmcnt(0)
	s_cbranch_scc0 .Lrw1_exitb
.LBB0_1094:
	v_add_u32_e32 v31, s76, v31
	v_add_u32_e32 v32, s76, v32
	s_waitcnt vmcnt(3)
	v_lshlrev_b32_e32 v2, 16, v14
	v_mul_f32_e32 v2, 0x3fb8aa3b, v2
	v_exp_f32_e32 v56, v2
	v_and_b32_e32 v2, 0xffff0000, v14
	v_mul_f32_e32 v2, 0x3fb8aa3b, v2
	v_exp_f32_e32 v57, v2
	v_lshlrev_b32_e32 v2, 16, v15
	v_mul_f32_e32 v2, 0x3fb8aa3b, v2
	v_exp_f32_e32 v58, v2
	v_and_b32_e32 v2, 0xffff0000, v15
	v_mul_f32_e32 v2, 0x3fb8aa3b, v2
	v_exp_f32_e32 v59, v2
	s_waitcnt vmcnt(2)
	v_and_b32_e32 v53, 0xffff0000, v16
	v_lshlrev_b32_e32 v52, 16, v16
	v_and_b32_e32 v55, 0xffff0000, v17
	v_lshlrev_b32_e32 v54, 16, v17
	ds_write_b128 v31, v[52:55]
	s_waitcnt vmcnt(1)
	v_and_b32_e32 v53, 0xffff0000, v20
	v_lshlrev_b32_e32 v52, 16, v20
	v_and_b32_e32 v55, 0xffff0000, v21
	v_lshlrev_b32_e32 v54, 16, v21
	s_waitcnt vmcnt(2)
	v_and_b32_e32 v2, 0xffff0000, v18
	v_lshlrev_b32_e32 v13, 16, v18
	ds_write_b128 v31, v[52:55] offset:8192
	ds_write_b128 v31, v[56:59] offset:4096
	v_xor_b32_e32 v53, 0x80000000, v2
	v_xor_b32_e32 v52, 0x80000000, v13
	v_and_b32_e32 v2, 0xffff0000, v19
	v_lshlrev_b32_e32 v13, 16, v19
	s_and_b32 s24, s10, 0x100
	v_xor_b32_e32 v55, 0x80000000, v2
	v_xor_b32_e32 v54, 0x80000000, v13
	v_ashrrev_i32_e32 v29, 31, v28
	ds_write_b128 v31, v[52:55] offset:12288
	s_waitcnt vmcnt(1)
	v_and_b32_e32 v53, 0xffff0000, v22
	v_lshlrev_b32_e32 v52, 16, v22
	v_and_b32_e32 v55, 0xffff0000, v23
	v_lshlrev_b32_e32 v54, 16, v23
	s_waitcnt vmcnt(0)
	v_lshlrev_b32_e32 v2, 16, v27
	s_cmp_eq_u32 s10, 0
	ds_write_b128 v31, v[52:55] offset:16384
	ds_write_b32 v32, v2 offset:20480
	s_waitcnt lgkmcnt(0)
	s_barrier
	v_add_u32_e32 v30, s76, v30
	v_add_u32_e32 v33, s76, v33
	s_mul_i32 s76, s76, -1
	v_add_u32_e32 v2, 0x5000, v33
	ds_read2_b32 v[92:93], v2 offset1:16
	ds_read_b128 v[52:55], v30 offset:12288
	ds_read_b128 v[56:59], v30 offset:12544
	ds_read_b128 v[60:63], v30 offset:4096
	ds_read_b128 v[64:67], v30 offset:4352
	ds_read_b128 v[68:71], v30 offset:16384
	ds_read_b128 v[72:75], v30 offset:16640
	ds_read_b128 v[76:79], v30 offset:8192
	ds_read_b128 v[80:83], v30 offset:8448
	ds_read_b128 v[84:87], v30
	ds_read_b128 v[88:91], v30 offset:256
	s_cbranch_scc1 .LBB0_1096
	s_xor_b32 s14, s24, 0x100
	v_lshl_add_u32 v2, s14, 2, v35
	ds_read_b32 v2, v2 offset:21504
	v_lshlrev_b64 v[122:123], 10, v[28:29]
	s_lshl_b32 s14, s9, 1
	v_lshl_add_u64 v[122:123], s[86:87], 0, v[122:123]
	v_lshl_add_u64 v[122:123], v[122:123], 0, s[14:15]
	s_waitcnt lgkmcnt(0)
	v_cvt_pk_bf16_f32 v13, v2, s0
	v_lshlrev_b32_e32 v2, 1, v10
	v_lshl_add_u64 v[122:123], v[122:123], 0, v[2:3]
	s_lshl_b32 s14, s2, 1
	v_lshl_add_u64 v[122:123], v[122:123], 0, s[14:15]
	v_add_co_u32_e32 v122, vcc, 0xffffc000, v122
	s_nop 1
	v_addc_co_u32_e32 v123, vcc, -1, v123, vcc
	global_store_short v[122:123], v13, off
.LBB0_1096:
	s_cmp_ge_u32 s3, s8
	s_cbranch_scc1 .LBB0_1093
	v_lshl_add_u64 v[14:15], v[28:29], 0, 16
	v_mov_b64_e32 v[16:17], s[46:47]
	v_mad_u64_u32 v[16:17], s[26:27], v14, s50, v[16:17]
	v_mad_i32_i24 v17, v15, s50, v17
	s_lshl_b32 s14, s2, 1
	v_lshl_add_u64 v[18:19], v[16:17], 0, s[14:15]
	v_mov_b32_e32 v13, v3
	v_lshl_add_u64 v[20:21], v[18:19], 0, v[12:13]
	v_mad_u64_u32 v[22:23], s[26:27], v14, s52, v[24:25]
	v_add_co_u32_e32 v122, vcc, s51, v20
	v_mad_i32_i24 v23, v15, s52, v23
	v_mov_b32_e32 v27, v3
	v_addc_co_u32_e32 v123, vcc, 0, v21, vcc
	global_load_dwordx2 v[14:15], v[22:23], off
	global_load_dwordx2 v[18:19], v[22:23], off offset:1024
	s_nop 0
	global_load_dwordx2 v[22:23], v[22:23], off offset:2048
	v_lshl_add_u64 v[124:125], v[16:17], 0, v[26:27]
	global_load_dwordx2 v[16:17], v[20:21], off offset:1024
	s_nop 0
	global_load_dwordx2 v[20:21], v[122:123], off offset:1024
	global_load_ushort v27, v[124:125], off
	s_branch .LBB0_1093
